# combined: GEMM K-loop B0 read rebalancing (6 loops) + hand-written P7 residual epilogue (5-deep prefetch) + packed-math P2b EpiAct epilogue + LRU gate weight loads hoisted into batches
# baseline (speedup 1.0000x reference)
; DEVI u16 f2bf(float x) { return (u16)(pk_bf16(x, 0.f) & 0xffffu); }
; DEVI void lru_item(const Params& p, int l, int item, int pass) {
;     ...
;   { const float* cw = p.in[11] + (size_t)l * 4 * 256 + c;
;     const float w0 = cw[0], w1 = cw[256], w2 = cw[512], w3 = cw[768], cb = p.in[12][l * 256 + c];
;     const float* xr = xs + e * 145 + 8 + 16 * tg;
; #pragma unroll
;     for (int tt = 0; tt < 16; ++tt) { const float u = cb + w0 * xr[tt - 2] + w1 * xr[tt - 1] + w2 * xr[tt] + w3 * xr[tt + 1]; uo[tt] = u; ub[(16 * tg + tt) * 72 + e] = f2bf(u); } }
.LBB0_1294:
	s_or_b64 exec, exec, s[4:5]
	v_and_b32_e32 v55, 63, v53
	v_readlane_b32 s44, v252, 30
	s_waitcnt vmcnt(0)
	v_or_b32_e32 v11, s13, v55
	v_readlane_b32 s52, v252, 38
	v_readlane_b32 s53, v252, 39
	v_or_b32_e32 v212, s36, v11
	s_mov_b64 s[16:17], s[52:53]
	v_lshlrev_b32_e32 v1, 2, v11
	v_lshl_add_u64 v[4:5], v[212:213], 2, s[16:17]
	s_waitcnt lgkmcnt(0)
	s_barrier
	global_load_dword v2, v1, s[22:23]
	global_load_dword v3, v1, s[22:23] offset:1024
	global_load_dword v0, v1, s[22:23] offset:2048
	s_nop 0
	global_load_dword v1, v1, s[22:23] offset:3072
	s_movk_i32 s1, 0x244
	global_load_dword v69, v[4:5], off
	v_mad_u32_u24 v6, v55, s1, 0
	v_and_b32_e32 v4, 0xffffffc0, v54
	v_add_u32_e32 v7, v6, v4
	ds_read2_b32 v[4:5], v7 offset0:6 offset1:7
	v_ashrrev_i32_e32 v52, 6, v54
	s_movk_i32 s1, 0x900
	v_mul_i32_i24_e32 v8, 0xfffffdbe, v55
	v_and_b32_e32 v10, 15, v53
	v_readlane_b32 s4, v252, 63
	v_and_b32_e32 v212, 48, v53
	v_readlane_b32 s5, v253, 0
	s_lshl_b32 s0, s0, 13
	s_or_b32 s90, s0, s41
	v_lshlrev_b32_e32 v73, 6, v10
	v_or_b32_e32 v34, s37, v11
	v_or_b32_e32 v13, 0x800, v73
	v_lshlrev_b32_e32 v30, 1, v13
	v_mov_b32_e32 v31, v213
	v_or_b32_e32 v13, 0xc00, v73
	v_lshlrev_b32_e32 v32, 1, v13
	v_mov_b32_e32 v33, v213
	v_bfe_u32 v82, v53, 4, 2
	s_movk_i32 s0, 0x410
	v_or_b32_e32 v35, 0x400, v73
	v_readlane_b32 s45, v252, 31
	v_readlane_b32 s46, v252, 32
	v_readlane_b32 s47, v252, 33
	v_readlane_b32 s48, v252, 34
	v_readlane_b32 s49, v252, 35
	v_readlane_b32 s50, v252, 36
	v_readlane_b32 s51, v252, 37
	v_readlane_b32 s54, v252, 40
	v_readlane_b32 s55, v252, 41
	v_readlane_b32 s56, v252, 42
	v_readlane_b32 s57, v252, 43
	v_readlane_b32 s58, v252, 44
	v_readlane_b32 s59, v252, 45
	s_mov_b64 s[20:21], s[56:57]
	v_readlane_b32 s44, v252, 46
	v_readlane_b32 s45, v252, 47
	v_readlane_b32 s46, v252, 48
	v_readlane_b32 s47, v252, 49
	v_readlane_b32 s48, v252, 50
	v_readlane_b32 s49, v252, 51
	v_readlane_b32 s50, v252, 52
	v_readlane_b32 s51, v252, 53
	v_readlane_b32 s52, v252, 54
	v_readlane_b32 s53, v252, 55
	v_readlane_b32 s54, v252, 56
	v_readlane_b32 s55, v252, 57
	v_readlane_b32 s56, v252, 58
	v_readlane_b32 s57, v252, 59
	v_readlane_b32 s58, v252, 60
	v_readlane_b32 s59, v252, 61
	s_waitcnt vmcnt(0) lgkmcnt(0)
	v_fma_f32 v56, v2, v4, v69
	v_fmac_f32_e32 v56, v3, v5
	ds_read2_b32 v[4:5], v7 offset0:8 offset1:9
	s_waitcnt lgkmcnt(0)
	v_fmac_f32_e32 v56, v0, v4
	v_fmac_f32_e32 v56, v1, v5
	v_mul_lo_u32 v5, v52, s1
	v_cvt_pk_bf16_f32 v4, v56, v213
	v_add3_u32 v6, v6, v8, v5
	ds_write_b16 v6, v4 offset:37120
	ds_read2_b32 v[4:5], v7 offset0:7 offset1:8
	s_movk_i32 s1, 0x90
	s_waitcnt lgkmcnt(0)
	v_fma_f32 v57, v2, v4, v69
	v_fmac_f32_e32 v57, v3, v5
	ds_read2_b32 v[4:5], v7 offset0:9 offset1:10
	s_waitcnt lgkmcnt(0)
	v_fmac_f32_e32 v57, v0, v4
	v_fmac_f32_e32 v57, v1, v5
	v_cvt_pk_bf16_f32 v4, v57, v213
	ds_write_b16 v6, v4 offset:37264
	ds_read2_b32 v[4:5], v7 offset0:8 offset1:9
	s_waitcnt lgkmcnt(0)
	v_fma_f32 v58, v2, v4, v69
	v_fmac_f32_e32 v58, v3, v5
	ds_read2_b32 v[4:5], v7 offset0:10 offset1:11
	s_waitcnt lgkmcnt(0)
	v_fmac_f32_e32 v58, v0, v4
	v_fmac_f32_e32 v58, v1, v5
	v_cvt_pk_bf16_f32 v4, v58, v213
	ds_write_b16 v6, v4 offset:37408
	ds_read2_b32 v[4:5], v7 offset0:9 offset1:10
	s_waitcnt lgkmcnt(0)
	v_fma_f32 v59, v2, v4, v69
	v_fmac_f32_e32 v59, v3, v5
	ds_read2_b32 v[4:5], v7 offset0:11 offset1:12
	s_waitcnt lgkmcnt(0)
	v_fmac_f32_e32 v59, v0, v4
	v_fmac_f32_e32 v59, v1, v5
	v_cvt_pk_bf16_f32 v4, v59, v213
	ds_write_b16 v6, v4 offset:37552
	ds_read2_b32 v[4:5], v7 offset0:10 offset1:11
	s_waitcnt lgkmcnt(0)
	v_fma_f32 v60, v2, v4, v69
	v_fmac_f32_e32 v60, v3, v5
	ds_read2_b32 v[4:5], v7 offset0:12 offset1:13
	s_waitcnt lgkmcnt(0)
	v_fmac_f32_e32 v60, v0, v4
	v_fmac_f32_e32 v60, v1, v5
	v_cvt_pk_bf16_f32 v4, v60, v213
	ds_write_b16 v6, v4 offset:37696
	ds_read2_b32 v[4:5], v7 offset0:11 offset1:12
	s_waitcnt lgkmcnt(0)
	v_fma_f32 v61, v2, v4, v69
	v_fmac_f32_e32 v61, v3, v5
	ds_read2_b32 v[4:5], v7 offset0:13 offset1:14
	s_waitcnt lgkmcnt(0)
	v_fmac_f32_e32 v61, v0, v4
	v_fmac_f32_e32 v61, v1, v5
	v_cvt_pk_bf16_f32 v4, v61, v213
	ds_write_b16 v6, v4 offset:37840
	ds_read2_b32 v[4:5], v7 offset0:12 offset1:13
	s_waitcnt lgkmcnt(0)
	v_fma_f32 v62, v2, v4, v69
	v_fmac_f32_e32 v62, v3, v5
	ds_read2_b32 v[4:5], v7 offset0:14 offset1:15
	s_waitcnt lgkmcnt(0)
	v_fmac_f32_e32 v62, v0, v4
	v_fmac_f32_e32 v62, v1, v5
	v_cvt_pk_bf16_f32 v4, v62, v213
	ds_write_b16 v6, v4 offset:37984
	ds_read2_b32 v[4:5], v7 offset0:13 offset1:14
	s_waitcnt lgkmcnt(0)
	v_fma_f32 v63, v2, v4, v69
	v_fmac_f32_e32 v63, v3, v5
	ds_read2_b32 v[4:5], v7 offset0:15 offset1:16
	s_waitcnt lgkmcnt(0)
	v_fmac_f32_e32 v63, v0, v4
	v_fmac_f32_e32 v63, v1, v5
	v_cvt_pk_bf16_f32 v4, v63, v213
	ds_write_b16 v6, v4 offset:38128
	ds_read2_b32 v[4:5], v7 offset0:14 offset1:15
	s_waitcnt lgkmcnt(0)
	v_fma_f32 v64, v2, v4, v69
	v_fmac_f32_e32 v64, v3, v5
	ds_read2_b32 v[4:5], v7 offset0:16 offset1:17
	s_waitcnt lgkmcnt(0)
	v_fmac_f32_e32 v64, v0, v4
	v_fmac_f32_e32 v64, v1, v5
	v_cvt_pk_bf16_f32 v4, v64, v213
	ds_write_b16 v6, v4 offset:38272
	ds_read2_b32 v[4:5], v7 offset0:15 offset1:16
	s_waitcnt lgkmcnt(0)
	v_fma_f32 v65, v2, v4, v69
	v_fmac_f32_e32 v65, v3, v5
	ds_read2_b32 v[4:5], v7 offset0:17 offset1:18
	s_waitcnt lgkmcnt(0)
	v_fmac_f32_e32 v65, v0, v4
	v_fmac_f32_e32 v65, v1, v5
	v_cvt_pk_bf16_f32 v4, v65, v213
	ds_write_b16 v6, v4 offset:38416
	ds_read2_b32 v[4:5], v7 offset0:16 offset1:17
	s_waitcnt lgkmcnt(0)
	v_fma_f32 v66, v2, v4, v69
	v_fmac_f32_e32 v66, v3, v5
	ds_read2_b32 v[4:5], v7 offset0:18 offset1:19
	s_waitcnt lgkmcnt(0)
; DEVI u16 f2bf(float x) { return (u16)(pk_bf16(x, 0.f) & 0xffffu); }
; DEVI f32x4 mfma16(bf16x8 a, bf16x8 b, f32x4 c) { return __builtin_amdgcn_mfma_f32_16x16x32_bf16(a, b, c, 0, 0, 0); }
; DEVI void lru_item(const Params& p, int l, int item, int pass) {
;     ...
;   { const float* cw = p.in[11] + (size_t)l * 4 * 256 + c;
;     const float w0 = cw[0], w1 = cw[256], w2 = cw[512], w3 = cw[768], cb = p.in[12][l * 256 + c];
;     const float* xr = xs + e * 145 + 8 + 16 * tg;
; #pragma unroll
;     for (int tt = 0; tt < 16; ++tt) { const float u = cb + w0 * xr[tt - 2] + w1 * xr[tt - 1] + w2 * xr[tt] + w3 * xr[tt + 1]; uo[tt] = u; ub[(16 * tg + tt) * 72 + e] = f2bf(u); } }
;     ...
;   const bf16x8 A0 = *(const bf16x8*)(ub + (16 * tg + fr) * 72 + 8 * g), A1 = *(const bf16x8*)(ub + (16 * tg + fr) * 72 + 32 + 8 * g);
;   const u16* WGT = (const u16*)(p.ws + OFF_WGT);
;   float* exw = ex + tg * 16 * 65;
;   float av[2][16], bv[2][16];
; #pragma unroll
;   for (int d = 0; d < 2; ++d) {
;     float pre[2][16];
; #pragma unroll
;     for (int mat = 0; mat < 2; ++mat) {
;       const u16* wb = WGT + (size_t)((((l * 2 + d) * 2 + mat) * 4 + n) * 64) * 64 + 8 * g;
;       f32x4 acc[4];
; #pragma unroll
;       for (int nt = 0; nt < 4; ++nt) {
;         const bf16x8 B0 = *(const bf16x8*)(wb + (16 * nt + fr) * 64), B1 = *(const bf16x8*)(wb + (16 * nt + fr) * 64 + 32);
;         f32x4 z = {0.f, 0.f, 0.f, 0.f};
;         z = mfma16(A0, B0, z); z = mfma16(A1, B1, z); acc[nt] = z;
;       }
;       asm volatile("s_waitcnt lgkmcnt(0)" ::: "memory");
; #pragma unroll
;       for (int nt = 0; nt < 4; ++nt)
; #pragma unroll
;         for (int j = 0; j < 4; ++j) exw[(4 * g + j) * 65 + 16 * nt + fr] = acc[nt][j];
;       asm volatile("s_waitcnt lgkmcnt(0)" ::: "memory");
; #pragma unroll
;       for (int tt = 0; tt < 16; ++tt) pre[mat][tt] = exw[tt * 65 + lane];
	v_fmac_f32_e32 v66, v0, v4
	v_fmac_f32_e32 v66, v1, v5
	v_cvt_pk_bf16_f32 v4, v66, v213
	ds_write_b16 v6, v4 offset:38560
	ds_read2_b32 v[4:5], v7 offset0:17 offset1:18
	s_waitcnt lgkmcnt(0)
	v_fma_f32 v67, v2, v4, v69
	v_fmac_f32_e32 v67, v3, v5
	ds_read2_b32 v[4:5], v7 offset0:19 offset1:20
	s_waitcnt lgkmcnt(0)
	v_fmac_f32_e32 v67, v0, v4
	v_fmac_f32_e32 v67, v1, v5
	v_cvt_pk_bf16_f32 v4, v67, v213
	ds_write_b16 v6, v4 offset:38704
	ds_read2_b32 v[4:5], v7 offset0:18 offset1:19
	s_waitcnt lgkmcnt(0)
	v_fma_f32 v68, v2, v4, v69
	v_fmac_f32_e32 v68, v3, v5
	ds_read2_b32 v[4:5], v7 offset0:20 offset1:21
	s_waitcnt lgkmcnt(0)
	v_fmac_f32_e32 v68, v0, v4
	v_fmac_f32_e32 v68, v1, v5
	v_cvt_pk_bf16_f32 v4, v68, v213
	ds_write_b16 v6, v4 offset:38848
	ds_read2_b32 v[4:5], v7 offset0:19 offset1:20
	s_waitcnt lgkmcnt(0)
	v_fma_f32 v70, v2, v4, v69
	v_fmac_f32_e32 v70, v3, v5
	ds_read2_b32 v[4:5], v7 offset0:21 offset1:22
	s_waitcnt lgkmcnt(0)
	v_fmac_f32_e32 v70, v0, v4
	v_fmac_f32_e32 v70, v1, v5
	v_cvt_pk_bf16_f32 v4, v70, v213
	ds_write_b16 v6, v4 offset:38992
	ds_read2_b32 v[4:5], v7 offset0:20 offset1:21
	s_waitcnt lgkmcnt(0)
	v_fma_f32 v71, v2, v4, v69
	v_fmac_f32_e32 v71, v3, v5
	ds_read2_b32 v[4:5], v7 offset0:22 offset1:23
	s_waitcnt lgkmcnt(0)
	v_fmac_f32_e32 v71, v0, v4
	v_fmac_f32_e32 v71, v1, v5
	v_cvt_pk_bf16_f32 v4, v71, v213
	ds_write_b16 v6, v4 offset:39136
	ds_read2_b32 v[4:5], v7 offset0:21 offset1:22
	s_waitcnt lgkmcnt(0)
	v_fmac_f32_e32 v69, v2, v4
	v_fmac_f32_e32 v69, v3, v5
	ds_read2_b32 v[2:3], v7 offset0:23 offset1:24
	s_waitcnt lgkmcnt(0)
	v_fmac_f32_e32 v69, v0, v2
	v_fmac_f32_e32 v69, v1, v3
	v_cvt_pk_bf16_f32 v0, v69, v213
	ds_write_b16 v6, v0 offset:39280
	v_lshl_or_b32 v0, v52, 4, v10
	v_mul_lo_u32 v0, v0, s1
	s_movk_i32 s1, 0x1040
	v_mul_lo_u32 v8, v52, s1
	v_add_u32_e32 v12, 0, v8
	v_lshl_add_u64 v[8:9], s[4:5], 0, v[212:213]
	v_add3_u32 v0, 0, v0, v212
	v_lshl_add_u64 v[28:29], v[8:9], 0, s[90:91]
	v_lshlrev_b32_e32 v212, 7, v10
	v_lshl_add_u64 v[18:19], v[28:29], 0, v[212:213]
	s_waitcnt lgkmcnt(0)
	s_barrier
	ds_read_b128 v[4:7], v0 offset:37120
	ds_read_b128 v[0:3], v0 offset:37184
	v_lshl_add_u32 v72, v10, 2, v12
	s_mov_b64 s[30:31], 0x1000
	v_lshl_add_u64 v[214:215], v[18:19], 0, s[30:31]
	s_mov_b64 s[30:31], 0x9000
	v_lshl_add_u64 v[216:217], v[18:19], 0, s[30:31]
	s_mov_b64 s[30:31], 0x11000
	v_lshl_add_u64 v[220:221], v[18:19], 0, s[30:31]
	s_mov_b64 s[30:31], 0x19000
	v_lshl_add_u64 v[222:223], v[18:19], 0, s[30:31]
	global_load_dwordx4 v[152:155], v[214:215], off offset:-4096
	global_load_dwordx4 v[156:159], v[214:215], off offset:-4032
	global_load_dwordx4 v[160:163], v[214:215], off offset:-2048
	global_load_dwordx4 v[164:167], v[214:215], off offset:-1984
	global_load_dwordx4 v[168:171], v[214:215], off
	global_load_dwordx4 v[172:175], v[214:215], off offset:64
	global_load_dwordx4 v[176:179], v[214:215], off offset:2048
	global_load_dwordx4 v[180:183], v[214:215], off offset:2112
	global_load_dwordx4 v[184:187], v[216:217], off offset:-4096
	global_load_dwordx4 v[188:191], v[216:217], off offset:-4032
	global_load_dwordx4 v[192:195], v[216:217], off offset:-2048
	global_load_dwordx4 v[196:199], v[216:217], off offset:-1984
	global_load_dwordx4 v[200:203], v[216:217], off
	global_load_dwordx4 v[204:207], v[216:217], off offset:64
	global_load_dwordx4 v[208:211], v[216:217], off offset:2048
	global_load_dwordx4 v[144:147], v[216:217], off offset:2112
	s_nop 0
	v_lshl_add_u64 v[22:23], v[28:29], 0, v[30:31]
	v_lshl_add_u64 v[26:27], v[28:29], 0, v[32:33]
	v_mad_u32_u24 v13, v82, s0, v72
	s_mov_b64 s[0:1], 0x8000
	v_lshl_add_u32 v12, v55, 2, v12
	v_add_u32_e32 v74, 0xd800, v12
	v_add_u32_e32 v75, 0xda00, v12
	v_add_u32_e32 v76, 0xdc00, v12
	v_add_u32_e32 v77, 0xde00, v12
	v_add_u32_e32 v78, 0xe000, v12
	s_waitcnt vmcnt(15) lgkmcnt(1)
	v_mfma_f32_16x16x32_bf16 v[8:11], v[4:7], v[152:155], 0
	v_add_u32_e32 v79, 0xe200, v12
	v_add_u32_e32 v80, 0xe400, v12
	v_add_u32_e32 v81, 0xe600, v12
	s_waitcnt vmcnt(14) lgkmcnt(0)
	v_mfma_f32_16x16x32_bf16 v[8:11], v[0:3], v[156:159], v[8:11]
	s_nop 0
	s_nop 0
	s_nop 0
	s_mov_b64 s[4:5], s[44:45]
	s_mov_b64 s[6:7], s[46:47]
	s_mov_b64 s[8:9], s[48:49]
	s_mov_b64 s[10:11], s[50:51]
	s_waitcnt vmcnt(13)
	v_mfma_f32_16x16x32_bf16 v[14:17], v[4:7], v[160:163], 0
	s_waitcnt vmcnt(12)
	v_mfma_f32_16x16x32_bf16 v[14:17], v[0:3], v[164:167], v[14:17]
	s_nop 0
	s_nop 0
	s_nop 0
	s_waitcnt vmcnt(11)
	v_mfma_f32_16x16x32_bf16 v[18:21], v[4:7], v[168:171], 0
	s_waitcnt vmcnt(10)
	v_mfma_f32_16x16x32_bf16 v[18:21], v[0:3], v[172:175], v[18:21]
	s_nop 0
	s_nop 0
	v_add_u32_e32 v26, 0xd800, v13
	v_add_u32_e32 v27, 0xdc00, v13
	s_waitcnt lgkmcnt(0)
	ds_write2_b32 v26, v8, v14 offset0:64 offset1:80
	ds_write2_b32 v26, v9, v15 offset0:129 offset1:145
	ds_write2_b32 v26, v10, v16 offset0:194 offset1:210
	s_waitcnt vmcnt(9)
	v_mfma_f32_16x16x32_bf16 v[22:25], v[4:7], v[176:179], 0
	s_waitcnt vmcnt(8)
	v_mfma_f32_16x16x32_bf16 v[22:25], v[0:3], v[180:183], v[22:25]
	ds_write2_b32 v27, v11, v17 offset0:3 offset1:19
	s_nop 6
	ds_write2_b32 v26, v18, v22 offset0:96 offset1:112
	ds_write2_b32 v26, v19, v23 offset0:161 offset1:177
	ds_write2_b32 v26, v20, v24 offset0:226 offset1:242
	ds_write2_b32 v27, v21, v25 offset0:35 offset1:51
	v_lshl_add_u64 v[18:19], v[28:29], 0, s[0:1]
	s_waitcnt lgkmcnt(0)
	v_lshl_add_u64 v[22:23], v[18:19], 0, v[212:213]
	ds_read2_b32 v[48:49], v74 offset0:64 offset1:129
	ds_read2_b32 v[44:45], v75 offset0:66 offset1:131
	ds_read2_b32 v[40:41], v76 offset0:68 offset1:133
	ds_read2_b32 v[24:25], v77 offset0:70 offset1:135
	ds_read2_b32 v[20:21], v78 offset0:72 offset1:137
	ds_read2_b32 v[16:17], v79 offset0:74 offset1:139
	ds_read2_b32 v[10:11], v80 offset0:76 offset1:141
	ds_read2_b32 v[8:9], v81 offset0:78 offset1:143
	s_nop 0
	s_nop 0
	s_waitcnt vmcnt(7)
; DEVI float sigmoidf_(float x) { return __builtin_amdgcn_rcpf(1.f + __expf(-x)); }
; DEVI f32x4 mfma16(bf16x8 a, bf16x8 b, f32x4 c) { return __builtin_amdgcn_mfma_f32_16x16x32_bf16(a, b, c, 0, 0, 0); }
; DEVI void lru_item(const Params& p, int l, int item, int pass) {
;     ...
;       const u16* wb = WGT + (size_t)((((l * 2 + d) * 2 + mat) * 4 + n) * 64) * 64 + 8 * g;
;       f32x4 acc[4];
; #pragma unroll
;       for (int nt = 0; nt < 4; ++nt) {
;         const bf16x8 B0 = *(const bf16x8*)(wb + (16 * nt + fr) * 64), B1 = *(const bf16x8*)(wb + (16 * nt + fr) * 64 + 32);
;         f32x4 z = {0.f, 0.f, 0.f, 0.f};
;         z = mfma16(A0, B0, z); z = mfma16(A1, B1, z); acc[nt] = z;
;       }
;       asm volatile("s_waitcnt lgkmcnt(0)" ::: "memory");
; #pragma unroll
;       for (int nt = 0; nt < 4; ++nt)
; #pragma unroll
;         for (int j = 0; j < 4; ++j) exw[(4 * g + j) * 65 + 16 * nt + fr] = acc[nt][j];
;       asm volatile("s_waitcnt lgkmcnt(0)" ::: "memory");
; #pragma unroll
;       for (int tt = 0; tt < 16; ++tt) pre[mat][tt] = exw[tt * 65 + lane];
;     }
;     const float ba = p.in[14][(l * 2 + d) * 256 + c], bx = p.in[16][(l * 2 + d) * 256 + c];
;     const float lam = p.in[17][(l * 2 + d) * 256 + c];
;     const float exl = __expf(-lam); const float sp = exl < 0.03f ? exl * (1.f - exl * (0.5f - exl * (0.33333334f - 0.25f * exl))) : __logf(1.f + exl);
;     float Ap = 1.f, Bp = 0.f;
; #pragma unroll
;     for (int q = 0; q < 16; ++q) {
;       const int tt = d == 0 ? q : 15 - q;
;       const float r = sigmoidf_(pre[0][tt] + ba), ig = sigmoidf_(pre[1][tt] + bx);
;       const float la = -8.f * r * sp;
;       const float a = __expf(la);
;       const float om = fmaxf(1.f - a * a, 0.f);
;       const float bb = sqrtf(om) * (ig * uo[tt]);
	v_mfma_f32_16x16x32_bf16 v[12:15], v[4:7], v[184:187], 0
	v_lshlrev_b32_e32 v212, 1, v35
	v_lshl_add_u64 v[22:23], v[18:19], 0, v[212:213]
	v_mov_b32_e32 v35, v213
	s_waitcnt vmcnt(6)
	v_mfma_f32_16x16x32_bf16 v[12:15], v[0:3], v[188:191], v[12:15]
	s_nop 0
	s_nop 0
	v_lshl_add_u64 v[22:23], v[18:19], 0, v[30:31]
	v_lshl_add_u64 v[18:19], v[18:19], 0, v[32:33]
	s_waitcnt vmcnt(5)
	v_mfma_f32_16x16x32_bf16 v[36:39], v[4:7], v[192:195], 0
	s_mov_b32 s0, 0x3cf5c28f
	s_waitcnt vmcnt(4)
	v_mfma_f32_16x16x32_bf16 v[36:39], v[0:3], v[196:199], v[36:39]
	s_nop 0
	s_nop 0
	s_waitcnt vmcnt(3)
	v_mfma_f32_16x16x32_bf16 v[84:87], v[4:7], v[200:203], 0
	s_waitcnt vmcnt(2)
	v_mfma_f32_16x16x32_bf16 v[84:87], v[0:3], v[204:207], v[84:87]
	s_nop 0
	s_nop 0
	s_waitcnt lgkmcnt(0)
	s_waitcnt vmcnt(1)
	v_mfma_f32_16x16x32_bf16 v[88:91], v[4:7], v[208:211], 0
	s_waitcnt vmcnt(0)
	v_mfma_f32_16x16x32_bf16 v[88:91], v[0:3], v[144:147], v[88:91]
	global_load_dwordx4 v[152:155], v[220:221], off offset:-4096
	global_load_dwordx4 v[156:159], v[220:221], off offset:-4032
	global_load_dwordx4 v[160:163], v[220:221], off offset:-2048
	global_load_dwordx4 v[164:167], v[220:221], off offset:-1984
	global_load_dwordx4 v[168:171], v[220:221], off
	global_load_dwordx4 v[172:175], v[220:221], off offset:64
	global_load_dwordx4 v[176:179], v[220:221], off offset:2048
	global_load_dwordx4 v[180:183], v[220:221], off offset:2112
	global_load_dwordx4 v[184:187], v[222:223], off offset:-4096
	global_load_dwordx4 v[188:191], v[222:223], off offset:-4032
	global_load_dwordx4 v[192:195], v[222:223], off offset:-2048
	global_load_dwordx4 v[196:199], v[222:223], off offset:-1984
	global_load_dwordx4 v[200:203], v[222:223], off
	global_load_dwordx4 v[204:207], v[222:223], off offset:64
	global_load_dwordx4 v[208:211], v[222:223], off offset:2048
	global_load_dwordx4 v[144:147], v[222:223], off offset:2112
	ds_write2_b32 v26, v12, v36 offset0:64 offset1:80
	ds_write2_b32 v26, v13, v37 offset0:129 offset1:145
	ds_write2_b32 v26, v14, v38 offset0:194 offset1:210
	ds_write2_b32 v27, v15, v39 offset0:3 offset1:19
	s_nop 3
	ds_write2_b32 v26, v84, v88 offset0:96 offset1:112
	ds_write2_b32 v26, v85, v89 offset0:161 offset1:177
	ds_write2_b32 v26, v86, v90 offset0:226 offset1:242
	ds_write2_b32 v27, v87, v91 offset0:35 offset1:51
	v_lshlrev_b64 v[38:39], 2, v[34:35]
	s_waitcnt lgkmcnt(0)
	v_lshl_add_u64 v[34:35], s[20:21], 0, v[38:39]
	v_lshl_add_u64 v[36:37], s[4:5], 0, v[38:39]
	v_lshl_add_u64 v[38:39], s[6:7], 0, v[38:39]
	ds_read2_b32 v[50:51], v74 offset0:64 offset1:129
	ds_read2_b32 v[46:47], v75 offset0:66 offset1:131
	ds_read2_b32 v[42:43], v76 offset0:68 offset1:133
	ds_read2_b32 v[26:27], v77 offset0:70 offset1:135
	ds_read2_b32 v[22:23], v78 offset0:72 offset1:137
	ds_read2_b32 v[18:19], v79 offset0:74 offset1:139
	ds_read2_b32 v[14:15], v80 offset0:76 offset1:141
	ds_read2_b32 v[12:13], v81 offset0:78 offset1:143
	global_load_dword v83, v[38:39], off
	global_load_dword v31, v[34:35], off
	global_load_dword v33, v[36:37], off
	s_waitcnt vmcnt(2)
	v_mul_f32_e32 v83, 0xbfb8aa3b, v83
	v_exp_f32_e32 v84, v83
	s_nop 0
	v_cmp_ngt_f32_e64 s[6:7], s0, v84
	s_and_saveexec_b64 s[0:1], s[6:7]
	s_xor_b64 s[4:5], exec, s[0:1]
	s_cbranch_execz .LBB0_1296
	v_add_f32_e32 v83, 1.0, v84
	v_cmp_gt_f32_e64 s[6:7], s63, v83
	s_mov_b32 s0, 0x3f317217
	s_nop 0
	v_cndmask_b32_e64 v84, 0, 32, s[6:7]
	v_ldexp_f32 v83, v83, v84
	v_log_f32_e32 v83, v83
	s_nop 0
	v_mul_f32_e32 v84, 0x3f317217, v83
	v_fma_f32 v84, v83, s0, -v84
	v_fmac_f32_e32 v84, 0x3377d1cf, v83
	s_mov_b32 s0, 0x7f800000
	v_fmac_f32_e32 v84, 0x3f317217, v83
	v_cmp_lt_f32_e64 s[8:9], |v83|, s0
	s_nop 1
	v_cndmask_b32_e64 v83, v83, v84, s[8:9]
	v_cndmask_b32_e64 v84, 0, v225, s[6:7]
	v_sub_f32_e32 v83, v83, v84
.LBB0_1296:
	s_andn2_saveexec_b64 s[4:5], s[4:5]
	v_mov_b32_e32 v83, 0x3eaaaaab
	v_fmamk_f32 v83, v84, 0xbe800000, v83
	v_fma_f32 v83, -v84, v83, 0.5
	v_fma_f32 v83, -v84, v83, 1.0
	v_mul_f32_e32 v83, v84, v83
	s_or_b64 exec, exec, s[4:5]
	s_waitcnt vmcnt(1) lgkmcnt(14)
	v_add_f32_e32 v48, v48, v31
	v_mul_f32_e32 v48, 0xbfb8aa3b, v48
	v_exp_f32_e32 v48, v48
	v_add_f32_e32 v49, v49, v31
	v_mul_f32_e32 v49, 0xbfb8aa3b, v49
	v_exp_f32_e32 v49, v49
	v_add_f32_e32 v48, 1.0, v48
	v_rcp_f32_e32 v48, v48
	s_waitcnt vmcnt(0) lgkmcnt(7)
	v_add_f32_e32 v50, v50, v33
	v_add_f32_e32 v49, 1.0, v49
	v_mul_f32_e32 v50, 0xbfb8aa3b, v50
	v_mul_f32_e32 v48, 0xc1000000, v48
	v_mul_f32_e32 v48, v48, v83
	v_mul_f32_e32 v48, 0x3fb8aa3b, v48
	v_exp_f32_e32 v48, v48
	v_rcp_f32_e32 v49, v49
	v_exp_f32_e32 v50, v50
	v_add_f32_e32 v44, v44, v31
	v_fma_f32 v84, -v48, v48, 1.0
	v_max_f32_e32 v84, 0, v84
	v_cmp_gt_f32_e64 s[6:7], s92, v84
	v_mul_f32_e32 v85, 0x4f800000, v84
	v_mul_f32_e32 v49, 0xc1000000, v49
	v_cndmask_b32_e64 v84, v84, v85, s[6:7]
	v_sqrt_f32_e32 v85, v84
	v_add_f32_e32 v50, 1.0, v50
	v_mul_f32_e32 v49, v49, v83
	v_rcp_f32_e32 v50, v50
	v_add_u32_e32 v86, -1, v85
	v_fma_f32 v87, -v86, v85, v84
	v_cmp_ge_f32_e64 s[8:9], 0, v87
	v_add_u32_e32 v87, 1, v85
	v_mul_f32_e32 v49, 0x3fb8aa3b, v49
	v_cndmask_b32_e64 v86, v85, v86, s[8:9]
	v_fma_f32 v85, -v87, v85, v84
	v_cmp_lt_f32_e64 s[8:9], 0, v85
	v_exp_f32_e32 v49, v49
	v_mul_f32_e32 v44, 0xbfb8aa3b, v44
	v_cndmask_b32_e64 v85, v86, v87, s[8:9]
	v_mul_f32_e32 v86, 0x37800000, v85
	v_cndmask_b32_e64 v85, v85, v86, s[6:7]
	v_cmp_class_f32_e64 s[6:7], v84, v235
	v_mul_f32_e32 v50, v56, v50
	v_exp_f32_e32 v44, v44
	v_cndmask_b32_e64 v84, v85, v84, s[6:7]
	v_mul_f32_e32 v50, v50, v84
	v_fma_f32 v84, -v49, v49, 1.0
	v_max_f32_e32 v84, 0, v84
	v_cmp_gt_f32_e64 s[6:7], s92, v84
	v_mul_f32_e32 v85, 0x4f800000, v84
	v_add_f32_e32 v44, 1.0, v44
	v_cndmask_b32_e64 v84, v84, v85, s[6:7]
	v_sqrt_f32_e32 v85, v84
	v_rcp_f32_e32 v44, v44
	v_add_f32_e32 v51, v51, v33
	v_mul_f32_e32 v51, 0xbfb8aa3b, v51
	v_exp_f32_e32 v51, v51
	v_add_u32_e32 v86, -1, v85
	v_mul_f32_e32 v44, 0xc1000000, v44
	v_fma_f32 v87, -v86, v85, v84
	v_mul_f32_e32 v44, v44, v83
	v_cmp_ge_f32_e64 s[8:9], 0, v87
	v_add_u32_e32 v87, 1, v85
	v_mul_f32_e32 v44, 0x3fb8aa3b, v44
	v_add_f32_e32 v51, 1.0, v51
	v_cndmask_b32_e64 v86, v85, v86, s[8:9]
	v_fma_f32 v85, -v87, v85, v84
	v_exp_f32_e32 v44, v44
	v_rcp_f32_e32 v51, v51
	v_cmp_lt_f32_e64 s[8:9], 0, v85
	v_fmac_f32_e32 v50, 0, v48
	v_add_f32_e32 v45, v45, v31
	v_cndmask_b32_e64 v85, v86, v87, s[8:9]
	v_mul_f32_e32 v86, 0x37800000, v85
	v_cndmask_b32_e64 v85, v85, v86, s[6:7]
	v_cmp_class_f32_e64 s[6:7], v84, v235
	v_mul_f32_e32 v50, v49, v50
	v_mul_f32_e32 v48, v48, v49
	v_fma_f32 v49, -v44, v44, 1.0
	v_mul_f32_e32 v45, 0xbfb8aa3b, v45
	v_cndmask_b32_e64 v84, v85, v84, s[6:7]
	v_mul_f32_e32 v51, v57, v51
	v_max_f32_e32 v49, 0, v49
	v_exp_f32_e32 v45, v45
	v_fmac_f32_e32 v50, v51, v84
	v_cmp_gt_f32_e64 s[6:7], s92, v49
	v_mul_f32_e32 v51, 0x4f800000, v49
	s_waitcnt lgkmcnt(6)
; DEVI float sigmoidf_(float x) { return __builtin_amdgcn_rcpf(1.f + __expf(-x)); }
; DEVI void lru_item(const Params& p, int l, int item, int pass) {
;     ...
;     for (int q = 0; q < 16; ++q) {
;       const int tt = d == 0 ? q : 15 - q;
;       const float r = sigmoidf_(pre[0][tt] + ba), ig = sigmoidf_(pre[1][tt] + bx);
;       const float la = -8.f * r * sp;
;       const float a = __expf(la);
;       const float om = fmaxf(1.f - a * a, 0.f);
;       const float bb = sqrtf(om) * (ig * uo[tt]);
;       av[d][tt] = a; bv[d][tt] = bb;
;       Bp = a * Bp + bb; Ap *= a;
	v_add_f32_e32 v46, v46, v33
	v_cndmask_b32_e64 v49, v49, v51, s[6:7]
	v_sqrt_f32_e32 v51, v49
	v_add_f32_e32 v45, 1.0, v45
	v_mul_f32_e32 v46, 0xbfb8aa3b, v46
	v_rcp_f32_e32 v45, v45
	v_exp_f32_e32 v46, v46
	v_add_u32_e32 v84, -1, v51
	v_fma_f32 v85, -v84, v51, v49
	v_cmp_ge_f32_e64 s[8:9], 0, v85
	v_add_u32_e32 v85, 1, v51
	v_mul_f32_e32 v45, 0xc1000000, v45
	v_add_f32_e32 v46, 1.0, v46
	v_cndmask_b32_e64 v84, v51, v84, s[8:9]
	v_fma_f32 v51, -v85, v51, v49
	v_mul_f32_e32 v45, v45, v83
	v_rcp_f32_e32 v46, v46
	v_cmp_lt_f32_e64 s[8:9], 0, v51
	v_mul_f32_e32 v45, 0x3fb8aa3b, v45
	v_exp_f32_e32 v45, v45
	v_cndmask_b32_e64 v51, v84, v85, s[8:9]
	v_mul_f32_e32 v84, 0x37800000, v51
	v_cndmask_b32_e64 v51, v51, v84, s[6:7]
	v_cmp_class_f32_e64 s[6:7], v49, v235
	v_add_f32_e32 v40, v40, v31
	v_mul_f32_e32 v46, v58, v46
	v_cndmask_b32_e64 v49, v51, v49, s[6:7]
	v_mul_f32_e32 v50, v44, v50
	v_mul_f32_e32 v40, 0xbfb8aa3b, v40
	v_fmac_f32_e32 v50, v46, v49
	v_add_f32_e32 v46, v47, v33
	v_fma_f32 v47, -v45, v45, 1.0
	v_exp_f32_e32 v40, v40
	v_max_f32_e32 v47, 0, v47
	v_mul_f32_e32 v44, v44, v48
	v_cmp_gt_f32_e64 s[6:7], s92, v47
	v_mul_f32_e32 v48, 0x4f800000, v47
	v_add_f32_e32 v40, 1.0, v40
	v_cndmask_b32_e64 v47, v47, v48, s[6:7]
	v_sqrt_f32_e32 v48, v47
	v_rcp_f32_e32 v40, v40
	v_mul_f32_e32 v46, 0xbfb8aa3b, v46
	v_exp_f32_e32 v46, v46
	v_add_u32_e32 v49, -1, v48
	v_fma_f32 v51, -v49, v48, v47
	v_mul_f32_e32 v40, 0xc1000000, v40
	v_cmp_ge_f32_e64 s[8:9], 0, v51
	v_add_u32_e32 v51, 1, v48
	v_mul_f32_e32 v40, v40, v83
	v_cndmask_b32_e64 v49, v48, v49, s[8:9]
	v_fma_f32 v48, -v51, v48, v47
	v_mul_f32_e32 v40, 0x3fb8aa3b, v40
	v_add_f32_e32 v46, 1.0, v46
	v_cmp_lt_f32_e64 s[8:9], 0, v48
	v_exp_f32_e32 v40, v40
	v_rcp_f32_e32 v46, v46
	v_cndmask_b32_e64 v48, v49, v51, s[8:9]
	v_mul_f32_e32 v49, 0x37800000, v48
	v_cndmask_b32_e64 v48, v48, v49, s[6:7]
	v_cmp_class_f32_e64 s[6:7], v47, v235
	v_add_f32_e32 v41, v41, v31
	v_mul_f32_e32 v44, v45, v44
	v_cndmask_b32_e64 v47, v48, v47, s[6:7]
	v_mul_f32_e32 v48, v45, v50
	v_fma_f32 v45, -v40, v40, 1.0
	v_mul_f32_e32 v41, 0xbfb8aa3b, v41
	v_mul_f32_e32 v46, v59, v46
	v_max_f32_e32 v45, 0, v45
	v_exp_f32_e32 v41, v41
	v_fmac_f32_e32 v48, v46, v47
	v_cmp_gt_f32_e64 s[6:7], s92, v45
	v_mul_f32_e32 v46, 0x4f800000, v45
	s_waitcnt lgkmcnt(5)
	v_add_f32_e32 v42, v42, v33
	v_cndmask_b32_e64 v45, v45, v46, s[6:7]
	v_sqrt_f32_e32 v46, v45
	v_add_f32_e32 v41, 1.0, v41
	v_mul_f32_e32 v42, 0xbfb8aa3b, v42
	v_rcp_f32_e32 v41, v41
	v_exp_f32_e32 v42, v42
	v_add_u32_e32 v47, -1, v46
	v_fma_f32 v49, -v47, v46, v45
	v_cmp_ge_f32_e64 s[8:9], 0, v49
	v_add_u32_e32 v49, 1, v46
	v_mul_f32_e32 v41, 0xc1000000, v41
	v_add_f32_e32 v42, 1.0, v42
	v_cndmask_b32_e64 v47, v46, v47, s[8:9]
	v_fma_f32 v46, -v49, v46, v45
	v_mul_f32_e32 v41, v41, v83
	v_rcp_f32_e32 v42, v42
	v_cmp_lt_f32_e64 s[8:9], 0, v46
	v_mul_f32_e32 v41, 0x3fb8aa3b, v41
	v_exp_f32_e32 v41, v41
	v_cndmask_b32_e64 v46, v47, v49, s[8:9]
	v_mul_f32_e32 v47, 0x37800000, v46
	v_cndmask_b32_e64 v46, v46, v47, s[6:7]
	v_cmp_class_f32_e64 s[6:7], v45, v235
	v_add_f32_e32 v24, v24, v31
	v_mul_f32_e32 v42, v60, v42
	v_cndmask_b32_e64 v45, v46, v45, s[6:7]
	v_mul_f32_e32 v46, v40, v48
	v_mul_f32_e32 v24, 0xbfb8aa3b, v24
	v_fmac_f32_e32 v46, v42, v45
	v_add_f32_e32 v42, v43, v33
	v_fma_f32 v43, -v41, v41, 1.0
	v_exp_f32_e32 v24, v24
	v_max_f32_e32 v43, 0, v43
	v_mul_f32_e32 v40, v40, v44
	v_cmp_gt_f32_e64 s[6:7], s92, v43
	v_mul_f32_e32 v44, 0x4f800000, v43
	v_add_f32_e32 v24, 1.0, v24
	v_cndmask_b32_e64 v43, v43, v44, s[6:7]
	v_sqrt_f32_e32 v44, v43
	v_rcp_f32_e32 v24, v24
	v_mul_f32_e32 v42, 0xbfb8aa3b, v42
	v_exp_f32_e32 v42, v42
	v_add_u32_e32 v45, -1, v44
	v_fma_f32 v47, -v45, v44, v43
	v_mul_f32_e32 v24, 0xc1000000, v24
	v_cmp_ge_f32_e64 s[8:9], 0, v47
	v_add_u32_e32 v47, 1, v44
	v_mul_f32_e32 v24, v24, v83
	v_cndmask_b32_e64 v45, v44, v45, s[8:9]
	v_fma_f32 v44, -v47, v44, v43
	v_mul_f32_e32 v24, 0x3fb8aa3b, v24
	v_add_f32_e32 v42, 1.0, v42
	v_cmp_lt_f32_e64 s[8:9], 0, v44
	v_exp_f32_e32 v24, v24
	v_rcp_f32_e32 v42, v42
	v_cndmask_b32_e64 v44, v45, v47, s[8:9]
	v_mul_f32_e32 v45, 0x37800000, v44
	v_cndmask_b32_e64 v44, v44, v45, s[6:7]
	v_cmp_class_f32_e64 s[6:7], v43, v235
	v_add_f32_e32 v25, v25, v31
	v_mul_f32_e32 v40, v41, v40
	v_cndmask_b32_e64 v43, v44, v43, s[6:7]
	v_mul_f32_e32 v44, v41, v46
	v_fma_f32 v41, -v24, v24, 1.0
	v_mul_f32_e32 v25, 0xbfb8aa3b, v25
	v_mul_f32_e32 v42, v61, v42
	v_max_f32_e32 v41, 0, v41
	v_exp_f32_e32 v25, v25
	v_fmac_f32_e32 v44, v42, v43
	v_cmp_gt_f32_e64 s[6:7], s92, v41
	v_mul_f32_e32 v42, 0x4f800000, v41
	s_waitcnt lgkmcnt(4)
; DEVI float sigmoidf_(float x) { return __builtin_amdgcn_rcpf(1.f + __expf(-x)); }
; DEVI void lru_item(const Params& p, int l, int item, int pass) {
;     ...
;     for (int q = 0; q < 16; ++q) {
;       const int tt = d == 0 ? q : 15 - q;
;       const float r = sigmoidf_(pre[0][tt] + ba), ig = sigmoidf_(pre[1][tt] + bx);
;       const float la = -8.f * r * sp;
;       const float a = __expf(la);
;       const float om = fmaxf(1.f - a * a, 0.f);
;       const float bb = sqrtf(om) * (ig * uo[tt]);
;       av[d][tt] = a; bv[d][tt] = bb;
;       Bp = a * Bp + bb; Ap *= a;
	v_add_f32_e32 v26, v26, v33
	v_cndmask_b32_e64 v41, v41, v42, s[6:7]
	v_sqrt_f32_e32 v42, v41
	v_add_f32_e32 v25, 1.0, v25
	v_mul_f32_e32 v26, 0xbfb8aa3b, v26
	v_rcp_f32_e32 v25, v25
	v_exp_f32_e32 v26, v26
	v_add_u32_e32 v43, -1, v42
	v_fma_f32 v45, -v43, v42, v41
	v_cmp_ge_f32_e64 s[8:9], 0, v45
	v_add_u32_e32 v45, 1, v42
	v_mul_f32_e32 v25, 0xc1000000, v25
	v_add_f32_e32 v26, 1.0, v26
	v_cndmask_b32_e64 v43, v42, v43, s[8:9]
	v_fma_f32 v42, -v45, v42, v41
	v_mul_f32_e32 v25, v25, v83
	v_rcp_f32_e32 v26, v26
	v_cmp_lt_f32_e64 s[8:9], 0, v42
	v_mul_f32_e32 v25, 0x3fb8aa3b, v25
	v_exp_f32_e32 v25, v25
	v_cndmask_b32_e64 v42, v43, v45, s[8:9]
	v_mul_f32_e32 v43, 0x37800000, v42
	v_cndmask_b32_e64 v42, v42, v43, s[6:7]
	v_cmp_class_f32_e64 s[6:7], v41, v235
	v_add_f32_e32 v20, v20, v31
	v_mul_f32_e32 v26, v62, v26
	v_cndmask_b32_e64 v41, v42, v41, s[6:7]
	v_mul_f32_e32 v42, v24, v44
	v_mul_f32_e32 v20, 0xbfb8aa3b, v20
	v_fmac_f32_e32 v42, v26, v41
	v_add_f32_e32 v26, v27, v33
	v_fma_f32 v27, -v25, v25, 1.0
	v_exp_f32_e32 v20, v20
	v_max_f32_e32 v27, 0, v27
	v_mul_f32_e32 v24, v24, v40
	v_cmp_gt_f32_e64 s[6:7], s92, v27
	v_mul_f32_e32 v40, 0x4f800000, v27
	v_add_f32_e32 v20, 1.0, v20
	v_cndmask_b32_e64 v27, v27, v40, s[6:7]
	v_sqrt_f32_e32 v40, v27
	v_rcp_f32_e32 v20, v20
	v_mul_f32_e32 v26, 0xbfb8aa3b, v26
	v_exp_f32_e32 v26, v26
	v_add_u32_e32 v41, -1, v40
	v_fma_f32 v43, -v41, v40, v27
	v_mul_f32_e32 v20, 0xc1000000, v20
	v_cmp_ge_f32_e64 s[8:9], 0, v43
	v_add_u32_e32 v43, 1, v40
	v_mul_f32_e32 v20, v20, v83
	v_cndmask_b32_e64 v41, v40, v41, s[8:9]
	v_fma_f32 v40, -v43, v40, v27
	v_mul_f32_e32 v20, 0x3fb8aa3b, v20
	v_add_f32_e32 v26, 1.0, v26
	v_cmp_lt_f32_e64 s[8:9], 0, v40
	v_exp_f32_e32 v20, v20
	v_rcp_f32_e32 v26, v26
	v_cndmask_b32_e64 v40, v41, v43, s[8:9]
	v_mul_f32_e32 v41, 0x37800000, v40
	v_cndmask_b32_e64 v40, v40, v41, s[6:7]
	v_cmp_class_f32_e64 s[6:7], v27, v235
	v_add_f32_e32 v21, v21, v31
	v_mul_f32_e32 v24, v25, v24
	v_cndmask_b32_e64 v27, v40, v27, s[6:7]
	v_mul_f32_e32 v40, v25, v42
	v_fma_f32 v25, -v20, v20, 1.0
	v_mul_f32_e32 v21, 0xbfb8aa3b, v21
	v_mul_f32_e32 v26, v63, v26
	v_max_f32_e32 v25, 0, v25
	v_exp_f32_e32 v21, v21
	v_fmac_f32_e32 v40, v26, v27
	v_cmp_gt_f32_e64 s[6:7], s92, v25
	v_mul_f32_e32 v26, 0x4f800000, v25
	s_waitcnt lgkmcnt(3)
	v_add_f32_e32 v22, v22, v33
	v_cndmask_b32_e64 v25, v25, v26, s[6:7]
	v_sqrt_f32_e32 v26, v25
	v_add_f32_e32 v21, 1.0, v21
	v_mul_f32_e32 v22, 0xbfb8aa3b, v22
	v_rcp_f32_e32 v21, v21
	v_exp_f32_e32 v22, v22
	v_add_u32_e32 v27, -1, v26
	v_fma_f32 v41, -v27, v26, v25
	v_cmp_ge_f32_e64 s[8:9], 0, v41
	v_add_u32_e32 v41, 1, v26
	v_mul_f32_e32 v21, 0xc1000000, v21
	v_add_f32_e32 v22, 1.0, v22
	v_cndmask_b32_e64 v27, v26, v27, s[8:9]
	v_fma_f32 v26, -v41, v26, v25
	v_mul_f32_e32 v21, v21, v83
	v_rcp_f32_e32 v22, v22
	v_cmp_lt_f32_e64 s[8:9], 0, v26
	v_mul_f32_e32 v21, 0x3fb8aa3b, v21
	v_exp_f32_e32 v21, v21
	v_cndmask_b32_e64 v26, v27, v41, s[8:9]
	v_mul_f32_e32 v27, 0x37800000, v26
	v_cndmask_b32_e64 v26, v26, v27, s[6:7]
	v_cmp_class_f32_e64 s[6:7], v25, v235
	v_add_f32_e32 v16, v16, v31
	v_mul_f32_e32 v22, v64, v22
	v_cndmask_b32_e64 v25, v26, v25, s[6:7]
	v_mul_f32_e32 v26, v20, v40
	v_mul_f32_e32 v16, 0xbfb8aa3b, v16
	v_fmac_f32_e32 v26, v22, v25
	v_add_f32_e32 v22, v23, v33
	v_fma_f32 v23, -v21, v21, 1.0
	v_exp_f32_e32 v16, v16
	v_max_f32_e32 v23, 0, v23
	v_mul_f32_e32 v20, v20, v24
	v_cmp_gt_f32_e64 s[6:7], s92, v23
	v_mul_f32_e32 v24, 0x4f800000, v23
	v_add_f32_e32 v16, 1.0, v16
	v_cndmask_b32_e64 v23, v23, v24, s[6:7]
	v_sqrt_f32_e32 v24, v23
	v_rcp_f32_e32 v16, v16
	v_mul_f32_e32 v22, 0xbfb8aa3b, v22
	v_exp_f32_e32 v22, v22
	v_add_u32_e32 v25, -1, v24
	v_fma_f32 v27, -v25, v24, v23
	v_mul_f32_e32 v16, 0xc1000000, v16
	v_cmp_ge_f32_e64 s[8:9], 0, v27
	v_add_u32_e32 v27, 1, v24
	v_mul_f32_e32 v16, v16, v83
	v_cndmask_b32_e64 v25, v24, v25, s[8:9]
	v_fma_f32 v24, -v27, v24, v23
	v_mul_f32_e32 v16, 0x3fb8aa3b, v16
	v_add_f32_e32 v22, 1.0, v22
	v_cmp_lt_f32_e64 s[8:9], 0, v24
	v_exp_f32_e32 v16, v16
	v_rcp_f32_e32 v22, v22
	v_cndmask_b32_e64 v24, v25, v27, s[8:9]
	v_mul_f32_e32 v25, 0x37800000, v24
	v_cndmask_b32_e64 v24, v24, v25, s[6:7]
	v_cmp_class_f32_e64 s[6:7], v23, v235
	v_add_f32_e32 v17, v17, v31
	v_mul_f32_e32 v20, v21, v20
	v_cndmask_b32_e64 v23, v24, v23, s[6:7]
	v_mul_f32_e32 v24, v21, v26
	v_fma_f32 v21, -v16, v16, 1.0
	v_mul_f32_e32 v17, 0xbfb8aa3b, v17
	v_mul_f32_e32 v22, v65, v22
	v_max_f32_e32 v21, 0, v21
	v_exp_f32_e32 v17, v17
	v_fmac_f32_e32 v24, v22, v23
	v_cmp_gt_f32_e64 s[6:7], s92, v21
	v_mul_f32_e32 v22, 0x4f800000, v21
	s_waitcnt lgkmcnt(2)
; DEVI float sigmoidf_(float x) { return __builtin_amdgcn_rcpf(1.f + __expf(-x)); }
; DEVI f32x4 mfma16(bf16x8 a, bf16x8 b, f32x4 c) { return __builtin_amdgcn_mfma_f32_16x16x32_bf16(a, b, c, 0, 0, 0); }
; DEVI void lru_item(const Params& p, int l, int item, int pass) {
;     ...
;       const u16* wb = WGT + (size_t)((((l * 2 + d) * 2 + mat) * 4 + n) * 64) * 64 + 8 * g;
;       f32x4 acc[4];
; #pragma unroll
;       for (int nt = 0; nt < 4; ++nt) {
;         const bf16x8 B0 = *(const bf16x8*)(wb + (16 * nt + fr) * 64), B1 = *(const bf16x8*)(wb + (16 * nt + fr) * 64 + 32);
;         f32x4 z = {0.f, 0.f, 0.f, 0.f};
;         z = mfma16(A0, B0, z); z = mfma16(A1, B1, z); acc[nt] = z;
;     ...
;     for (int q = 0; q < 16; ++q) {
;       const int tt = d == 0 ? q : 15 - q;
;       const float r = sigmoidf_(pre[0][tt] + ba), ig = sigmoidf_(pre[1][tt] + bx);
;       const float la = -8.f * r * sp;
;       const float a = __expf(la);
;       const float om = fmaxf(1.f - a * a, 0.f);
;       const float bb = sqrtf(om) * (ig * uo[tt]);
;       av[d][tt] = a; bv[d][tt] = bb;
;       Bp = a * Bp + bb; Ap *= a;
;     }
;     sm[((d * 8 + tg) * 64 + e) * 2 + 0] = Ap; sm[((d * 8 + tg) * 64 + e) * 2 + 1] = Bp;
	v_add_f32_e32 v18, v18, v33
	v_cndmask_b32_e64 v21, v21, v22, s[6:7]
	v_sqrt_f32_e32 v22, v21
	v_add_f32_e32 v17, 1.0, v17
	v_mul_f32_e32 v18, 0xbfb8aa3b, v18
	v_rcp_f32_e32 v17, v17
	v_exp_f32_e32 v18, v18
	v_add_u32_e32 v23, -1, v22
	v_fma_f32 v25, -v23, v22, v21
	v_cmp_ge_f32_e64 s[8:9], 0, v25
	v_add_u32_e32 v25, 1, v22
	v_mul_f32_e32 v17, 0xc1000000, v17
	v_add_f32_e32 v18, 1.0, v18
	v_cndmask_b32_e64 v23, v22, v23, s[8:9]
	v_fma_f32 v22, -v25, v22, v21
	v_mul_f32_e32 v17, v17, v83
	v_rcp_f32_e32 v18, v18
	v_cmp_lt_f32_e64 s[8:9], 0, v22
	v_mul_f32_e32 v17, 0x3fb8aa3b, v17
	v_exp_f32_e32 v17, v17
	v_cndmask_b32_e64 v22, v23, v25, s[8:9]
	v_mul_f32_e32 v23, 0x37800000, v22
	v_cndmask_b32_e64 v22, v22, v23, s[6:7]
	v_cmp_class_f32_e64 s[6:7], v21, v235
	v_add_f32_e32 v10, v10, v31
	v_mul_f32_e32 v18, v66, v18
	v_cndmask_b32_e64 v21, v22, v21, s[6:7]
	v_mul_f32_e32 v22, v16, v24
	v_mul_f32_e32 v10, 0xbfb8aa3b, v10
	v_fmac_f32_e32 v22, v18, v21
	v_add_f32_e32 v18, v19, v33
	v_fma_f32 v19, -v17, v17, 1.0
	v_exp_f32_e32 v10, v10
	v_max_f32_e32 v19, 0, v19
	v_mul_f32_e32 v16, v16, v20
	v_cmp_gt_f32_e64 s[6:7], s92, v19
	v_mul_f32_e32 v20, 0x4f800000, v19
	v_add_f32_e32 v10, 1.0, v10
	v_cndmask_b32_e64 v19, v19, v20, s[6:7]
	v_sqrt_f32_e32 v20, v19
	v_rcp_f32_e32 v10, v10
	v_mul_f32_e32 v18, 0xbfb8aa3b, v18
	v_exp_f32_e32 v18, v18
	v_add_u32_e32 v21, -1, v20
	v_fma_f32 v23, -v21, v20, v19
	v_mul_f32_e32 v10, 0xc1000000, v10
	v_cmp_ge_f32_e64 s[8:9], 0, v23
	v_add_u32_e32 v23, 1, v20
	v_mul_f32_e32 v10, v10, v83
	v_cndmask_b32_e64 v21, v20, v21, s[8:9]
	v_fma_f32 v20, -v23, v20, v19
	v_mul_f32_e32 v10, 0x3fb8aa3b, v10
	v_add_f32_e32 v18, 1.0, v18
	v_cmp_lt_f32_e64 s[8:9], 0, v20
	v_exp_f32_e32 v10, v10
	v_rcp_f32_e32 v18, v18
	v_cndmask_b32_e64 v20, v21, v23, s[8:9]
	v_mul_f32_e32 v21, 0x37800000, v20
	v_cndmask_b32_e64 v20, v20, v21, s[6:7]
	v_cmp_class_f32_e64 s[6:7], v19, v235
	v_add_f32_e32 v11, v11, v31
	v_mul_f32_e32 v16, v17, v16
	v_cndmask_b32_e64 v19, v20, v19, s[6:7]
	v_mul_f32_e32 v20, v17, v22
	v_fma_f32 v17, -v10, v10, 1.0
	v_mul_f32_e32 v11, 0xbfb8aa3b, v11
	v_mul_f32_e32 v18, v67, v18
	v_max_f32_e32 v17, 0, v17
	v_exp_f32_e32 v11, v11
	v_fmac_f32_e32 v20, v18, v19
	v_cmp_gt_f32_e64 s[6:7], s92, v17
	v_mul_f32_e32 v18, 0x4f800000, v17
	s_waitcnt lgkmcnt(1)
	v_add_f32_e32 v14, v14, v33
	v_cndmask_b32_e64 v17, v17, v18, s[6:7]
	v_sqrt_f32_e32 v18, v17
	v_add_f32_e32 v11, 1.0, v11
	v_mul_f32_e32 v14, 0xbfb8aa3b, v14
	v_rcp_f32_e32 v11, v11
	v_exp_f32_e32 v14, v14
	v_add_u32_e32 v19, -1, v18
	v_fma_f32 v21, -v19, v18, v17
	v_cmp_ge_f32_e64 s[8:9], 0, v21
	v_add_u32_e32 v21, 1, v18
	v_mul_f32_e32 v11, 0xc1000000, v11
	v_add_f32_e32 v14, 1.0, v14
	v_cndmask_b32_e64 v19, v18, v19, s[8:9]
	v_fma_f32 v18, -v21, v18, v17
	v_mul_f32_e32 v11, v11, v83
	v_rcp_f32_e32 v14, v14
	v_cmp_lt_f32_e64 s[8:9], 0, v18
	v_mul_f32_e32 v11, 0x3fb8aa3b, v11
	v_exp_f32_e32 v11, v11
	v_cndmask_b32_e64 v18, v19, v21, s[8:9]
	v_mul_f32_e32 v19, 0x37800000, v18
	v_cndmask_b32_e64 v18, v18, v19, s[6:7]
	v_cmp_class_f32_e64 s[6:7], v17, v235
	v_add_f32_e32 v8, v8, v31
	v_mul_f32_e32 v14, v68, v14
	v_cndmask_b32_e64 v17, v18, v17, s[6:7]
	v_mul_f32_e32 v18, v10, v20
	v_mul_f32_e32 v8, 0xbfb8aa3b, v8
	v_fmac_f32_e32 v18, v14, v17
	v_add_f32_e32 v14, v15, v33
	v_fma_f32 v15, -v11, v11, 1.0
	v_exp_f32_e32 v8, v8
	v_max_f32_e32 v15, 0, v15
	v_mul_f32_e32 v10, v10, v16
	v_cmp_gt_f32_e64 s[6:7], s92, v15
	v_mul_f32_e32 v16, 0x4f800000, v15
	v_add_f32_e32 v8, 1.0, v8
	v_cndmask_b32_e64 v15, v15, v16, s[6:7]
	v_sqrt_f32_e32 v16, v15
	v_rcp_f32_e32 v8, v8
	v_mul_f32_e32 v14, 0xbfb8aa3b, v14
	v_exp_f32_e32 v14, v14
	v_add_u32_e32 v17, -1, v16
	v_fma_f32 v19, -v17, v16, v15
	v_mul_f32_e32 v8, 0xc1000000, v8
	v_cmp_ge_f32_e64 s[8:9], 0, v19
	v_add_u32_e32 v19, 1, v16
	v_mul_f32_e32 v8, v8, v83
	v_cndmask_b32_e64 v17, v16, v17, s[8:9]
	v_fma_f32 v16, -v19, v16, v15
	v_mul_f32_e32 v8, 0x3fb8aa3b, v8
	v_add_f32_e32 v14, 1.0, v14
	v_cmp_lt_f32_e64 s[8:9], 0, v16
	v_exp_f32_e32 v8, v8
	v_rcp_f32_e32 v14, v14
	v_cndmask_b32_e64 v16, v17, v19, s[8:9]
	v_mul_f32_e32 v17, 0x37800000, v16
	v_cndmask_b32_e64 v16, v16, v17, s[6:7]
	v_cmp_class_f32_e64 s[6:7], v15, v235
	v_mul_f32_e32 v10, v11, v10
	v_mul_f32_e32 v14, v70, v14
	v_cndmask_b32_e64 v15, v16, v15, s[6:7]
	v_mul_f32_e32 v16, v11, v18
	s_waitcnt lgkmcnt(0)
	v_add_f32_e32 v11, v12, v33
	v_fma_f32 v12, -v8, v8, 1.0
	v_max_f32_e32 v12, 0, v12
	v_fmac_f32_e32 v16, v14, v15
	v_cmp_gt_f32_e64 s[6:7], s92, v12
	v_mul_f32_e32 v14, 0x4f800000, v12
	v_add_f32_e32 v9, v9, v31
	v_cndmask_b32_e64 v12, v12, v14, s[6:7]
	v_sqrt_f32_e32 v14, v12
	v_mul_f32_e32 v9, 0xbfb8aa3b, v9
	v_exp_f32_e32 v9, v9
	v_mul_f32_e32 v11, 0xbfb8aa3b, v11
	v_exp_f32_e32 v11, v11
	v_add_u32_e32 v15, -1, v14
	v_fma_f32 v17, -v15, v14, v12
	v_add_f32_e32 v9, 1.0, v9
	v_cmp_ge_f32_e64 s[8:9], 0, v17
	v_add_u32_e32 v17, 1, v14
	v_rcp_f32_e32 v9, v9
	v_add_f32_e32 v11, 1.0, v11
	v_cndmask_b32_e64 v15, v14, v15, s[8:9]
	v_fma_f32 v14, -v17, v14, v12
	v_rcp_f32_e32 v11, v11
	v_cmp_lt_f32_e64 s[8:9], 0, v14
	v_mul_f32_e32 v9, 0xc1000000, v9
	v_mul_f32_e32 v9, v9, v83
	v_cndmask_b32_e64 v14, v15, v17, s[8:9]
	v_mul_f32_e32 v15, 0x37800000, v14
	v_cndmask_b32_e64 v14, v14, v15, s[6:7]
	v_cmp_class_f32_e64 s[6:7], v12, v235
	v_mul_f32_e32 v11, v71, v11
	v_mul_f32_e32 v9, 0x3fb8aa3b, v9
	v_cndmask_b32_e64 v12, v14, v12, s[6:7]
	v_mul_f32_e32 v14, v8, v16
	v_fmac_f32_e32 v14, v11, v12
	v_exp_f32_e32 v11, v9
	v_mul_f32_e32 v8, v8, v10
	v_add_f32_e32 v10, v13, v33
	v_mul_f32_e32 v10, 0xbfb8aa3b, v10
	v_fma_f32 v9, -v11, v11, 1.0
	v_max_f32_e32 v9, 0, v9
	v_cmp_gt_f32_e64 s[6:7], s92, v9
	v_mul_f32_e32 v12, 0x4f800000, v9
	v_exp_f32_e32 v10, v10
	v_cndmask_b32_e64 v9, v9, v12, s[6:7]
	v_sqrt_f32_e32 v12, v9
	s_mov_b64 s[0:1], 0x10000
	v_add_f32_e32 v10, 1.0, v10
	v_rcp_f32_e32 v10, v10
	v_add_u32_e32 v13, -1, v12
	v_fma_f32 v15, -v13, v12, v9
	v_cmp_ge_f32_e64 s[8:9], 0, v15
	v_add_u32_e32 v15, 1, v12
	v_mul_f32_e32 v10, v69, v10
	v_cndmask_b32_e64 v13, v12, v13, s[8:9]
	v_fma_f32 v12, -v15, v12, v9
	v_cmp_lt_f32_e64 s[8:9], 0, v12
	v_mul_f32_e32 v8, v11, v8
	v_lshl_add_u64 v[24:25], v[28:29], 0, s[0:1]
	v_cndmask_b32_e64 v12, v13, v15, s[8:9]
	v_mul_f32_e32 v13, 0x37800000, v12
	v_cndmask_b32_e64 v12, v12, v13, s[6:7]
	v_cmp_class_f32_e64 s[6:7], v9, v235
	v_lshlrev_b32_e32 v40, 1, v73
	v_mov_b32_e32 v41, v213
	v_cndmask_b32_e64 v12, v12, v9, s[6:7]
	v_mul_f32_e32 v9, v11, v14
	v_fmac_f32_e32 v9, v10, v12
	v_lshlrev_b32_e32 v10, 3, v54
	v_add_u32_e32 v44, 0, v10
	v_add_u32_e32 v10, 0x15b00, v44
	ds_write_b64 v10, v[8:9]
	v_lshl_add_u64 v[12:13], v[24:25], 0, v[40:41]
	s_nop 0
	s_nop 0
	s_nop 0
	s_waitcnt vmcnt(18)
; DEVI f32x4 mfma16(bf16x8 a, bf16x8 b, f32x4 c) { return __builtin_amdgcn_mfma_f32_16x16x32_bf16(a, b, c, 0, 0, 0); }
; DEVI void lru_item(const Params& p, int l, int item, int pass) {
;     ...
;       const u16* wb = WGT + (size_t)((((l * 2 + d) * 2 + mat) * 4 + n) * 64) * 64 + 8 * g;
;       f32x4 acc[4];
; #pragma unroll
;       for (int nt = 0; nt < 4; ++nt) {
;         const bf16x8 B0 = *(const bf16x8*)(wb + (16 * nt + fr) * 64), B1 = *(const bf16x8*)(wb + (16 * nt + fr) * 64 + 32);
;         f32x4 z = {0.f, 0.f, 0.f, 0.f};
;         z = mfma16(A0, B0, z); z = mfma16(A1, B1, z); acc[nt] = z;
;       }
;       asm volatile("s_waitcnt lgkmcnt(0)" ::: "memory");
; #pragma unroll
;       for (int nt = 0; nt < 4; ++nt)
; #pragma unroll
;         for (int j = 0; j < 4; ++j) exw[(4 * g + j) * 65 + 16 * nt + fr] = acc[nt][j];
;       asm volatile("s_waitcnt lgkmcnt(0)" ::: "memory");
; #pragma unroll
;       for (int tt = 0; tt < 16; ++tt) pre[mat][tt] = exw[tt * 65 + lane];
;     }
;     const float ba = p.in[14][(l * 2 + d) * 256 + c], bx = p.in[16][(l * 2 + d) * 256 + c];
;     const float lam = p.in[17][(l * 2 + d) * 256 + c];
;     const float exl = __expf(-lam); const float sp = exl < 0.03f ? exl * (1.f - exl * (0.5f - exl * (0.33333334f - 0.25f * exl))) : __logf(1.f + exl);
	v_mfma_f32_16x16x32_bf16 v[8:11], v[4:7], v[152:155], 0
	v_lshl_add_u64 v[16:17], v[24:25], 0, v[212:213]
	v_mov_b32_e32 v31, v213
	v_lshl_add_u64 v[20:21], v[24:25], 0, v[30:31]
	s_waitcnt vmcnt(17)
	v_mfma_f32_16x16x32_bf16 v[8:11], v[0:3], v[156:159], v[8:11]
	s_nop 0
	s_nop 0
	s_nop 0
	v_mov_b32_e32 v33, v213
	v_lshl_add_u64 v[24:25], v[24:25], 0, v[32:33]
	s_waitcnt vmcnt(16)
	v_mfma_f32_16x16x32_bf16 v[12:15], v[4:7], v[160:163], 0
	v_mul_u32_u24_e32 v82, 0x410, v82
	s_mov_b64 s[0:1], 0x18000
	s_waitcnt vmcnt(15)
	v_mfma_f32_16x16x32_bf16 v[12:15], v[0:3], v[164:167], v[12:15]
	s_nop 0
	s_nop 0
	s_nop 0
	s_waitcnt vmcnt(14)
	v_mfma_f32_16x16x32_bf16 v[16:19], v[4:7], v[168:171], 0
	s_waitcnt vmcnt(13)
	v_mfma_f32_16x16x32_bf16 v[16:19], v[0:3], v[172:175], v[16:19]
	s_nop 0
	s_nop 0
	s_nop 0
	s_waitcnt lgkmcnt(0)
	s_waitcnt vmcnt(12)
	v_mfma_f32_16x16x32_bf16 v[20:23], v[4:7], v[176:179], 0
	s_waitcnt vmcnt(11)
	v_mfma_f32_16x16x32_bf16 v[20:23], v[0:3], v[180:183], v[20:23]
	v_add_u32_e32 v24, v72, v82
	v_add_u32_e32 v45, 0xd800, v24
	v_add_u32_e32 v50, 0xdc00, v24
	ds_write2_b32 v45, v8, v12 offset0:64 offset1:80
	ds_write2_b32 v45, v9, v13 offset0:129 offset1:145
	ds_write2_b32 v45, v10, v14 offset0:194 offset1:210
	ds_write2_b32 v50, v11, v15 offset0:3 offset1:19
	s_nop 0
	ds_write2_b32 v45, v16, v20 offset0:96 offset1:112
	ds_write2_b32 v45, v17, v21 offset0:161 offset1:177
	ds_write2_b32 v45, v18, v22 offset0:226 offset1:242
	ds_write2_b32 v50, v19, v23 offset0:35 offset1:51
	v_lshl_add_u64 v[18:19], v[28:29], 0, s[0:1]
	s_waitcnt lgkmcnt(0)
	v_lshl_add_u64 v[22:23], v[18:19], 0, v[40:41]
	ds_read2_b32 v[8:9], v74 offset0:64 offset1:129
	ds_read2_b32 v[10:11], v75 offset0:66 offset1:131
	ds_read2_b32 v[12:13], v76 offset0:68 offset1:133
	ds_read2_b32 v[14:15], v77 offset0:70 offset1:135
	ds_read2_b32 v[16:17], v78 offset0:72 offset1:137
	ds_read2_b32 v[20:21], v79 offset0:74 offset1:139
	ds_read2_b32 v[24:25], v80 offset0:76 offset1:141
	ds_read2_b32 v[42:43], v81 offset0:78 offset1:143
	s_nop 0
	s_nop 0
	s_waitcnt vmcnt(10)
	v_mfma_f32_16x16x32_bf16 v[26:29], v[4:7], v[184:187], 0
	v_lshl_add_u64 v[22:23], v[18:19], 0, v[212:213]
	s_mov_b32 s0, 0x3cf5c28f
	s_waitcnt vmcnt(9)
	v_mfma_f32_16x16x32_bf16 v[26:29], v[0:3], v[188:191], v[26:29]
	s_nop 0
	s_nop 0
	v_lshl_add_u64 v[22:23], v[18:19], 0, v[30:31]
	v_lshl_add_u64 v[18:19], v[18:19], 0, v[32:33]
	s_waitcnt vmcnt(8)
	v_mfma_f32_16x16x32_bf16 v[46:49], v[4:7], v[192:195], 0
	s_waitcnt vmcnt(7)
	v_mfma_f32_16x16x32_bf16 v[46:49], v[0:3], v[196:199], v[46:49]
	s_nop 0
	s_nop 0
	s_waitcnt vmcnt(6)
	v_mfma_f32_16x16x32_bf16 v[82:85], v[4:7], v[200:203], 0
	s_waitcnt vmcnt(5)
	v_mfma_f32_16x16x32_bf16 v[82:85], v[0:3], v[204:207], v[82:85]
	s_nop 0
	s_nop 0
	s_waitcnt lgkmcnt(0)
	s_waitcnt vmcnt(4)
	v_mfma_f32_16x16x32_bf16 v[4:7], v[4:7], v[208:211], 0
	s_waitcnt vmcnt(3)
	v_mfma_f32_16x16x32_bf16 v[0:3], v[0:3], v[144:147], v[4:7]
	ds_write2_b32 v45, v26, v46 offset0:64 offset1:80
	ds_write2_b32 v45, v27, v47 offset0:129 offset1:145
	ds_write2_b32 v45, v28, v48 offset0:194 offset1:210
	ds_write2_b32 v50, v29, v49 offset0:3 offset1:19
	s_nop 3
	ds_write2_b32 v45, v82, v0 offset0:96 offset1:112
	ds_write2_b32 v45, v83, v1 offset0:161 offset1:177
	ds_write2_b32 v45, v84, v2 offset0:226 offset1:242
	ds_write2_b32 v50, v85, v3 offset0:35 offset1:51
	s_waitcnt lgkmcnt(0)
	ds_read2_b32 v[0:1], v74 offset0:64 offset1:129
	ds_read2_b32 v[2:3], v75 offset0:66 offset1:131
	ds_read2_b32 v[4:5], v76 offset0:68 offset1:133
	ds_read2_b32 v[6:7], v77 offset0:70 offset1:135
	ds_read2_b32 v[18:19], v78 offset0:72 offset1:137
	ds_read2_b32 v[22:23], v79 offset0:74 offset1:139
	ds_read2_b32 v[26:27], v80 offset0:76 offset1:141
	ds_read2_b32 v[28:29], v81 offset0:78 offset1:143
	global_load_dword v31, v[34:35], off offset:1024
	global_load_dword v30, v[36:37], off offset:1024
	global_load_dword v32, v[38:39], off offset:1024
	s_waitcnt vmcnt(0)
	v_mul_f32_e32 v32, 0xbfb8aa3b, v32
	v_exp_f32_e32 v33, v32
	s_nop 0
	v_cmp_ngt_f32_e64 s[6:7], s0, v33
	s_and_saveexec_b64 s[0:1], s[6:7]
	s_xor_b64 s[4:5], exec, s[0:1]
	s_cbranch_execz .LBB0_1300
	v_add_f32_e32 v32, 1.0, v33
	v_cmp_gt_f32_e64 s[6:7], s63, v32
	s_mov_b32 s0, 0x3f317217
	s_nop 0
	v_cndmask_b32_e64 v33, 0, 32, s[6:7]
	v_ldexp_f32 v32, v32, v33
	v_log_f32_e32 v32, v32
	s_nop 0
	v_mul_f32_e32 v33, 0x3f317217, v32
	v_fma_f32 v33, v32, s0, -v33
	v_fmac_f32_e32 v33, 0x3377d1cf, v32
	s_mov_b32 s0, 0x7f800000
	v_fmac_f32_e32 v33, 0x3f317217, v32
	v_cmp_lt_f32_e64 s[8:9], |v32|, s0
	s_nop 1
	v_cndmask_b32_e64 v32, v32, v33, s[8:9]
	v_cndmask_b32_e64 v33, 0, v225, s[6:7]
	v_sub_f32_e32 v32, v32, v33

; DEVI float bf2f(u16 h) { return __uint_as_float(((unsigned)h) << 16); }
; DEVI f32x4 mfma16(bf16x8 a, bf16x8 b, f32x4 c) { return __builtin_amdgcn_mfma_f32_16x16x32_bf16(a, b, c, 0, 0, 0); }
; DEVI void lru_item(const Params& p, int l, int item, int pass) {
;     ...
;   if (pass) {
;     bf16x8 gv2[2];
; #pragma unroll
;     for (int i = 0; i < 2; ++i) { const int idx = tid + i * NTHREADS, chn = idx >> 4, ck = idx & 15; gv2[i] = *(const bf16x8*)(PT + (size_t)(256 + n * 64 + chn) * T + rowbase + t0 + ck * 8); }
; #pragma unroll
;     for (int i = 0; i < 2; ++i) { const int idx = tid + i * NTHREADS, chn = idx >> 4, ck = idx & 15;
; #pragma unroll
;       for (int q = 0; q < 8; ++q) xs[chn * 145 + 8 + ck * 8 + q] = bf2f((u16)gv2[i][q]); }
;   }
;   const bf16x8 A0 = *(const bf16x8*)(ub + (16 * tg + fr) * 72 + 8 * g), A1 = *(const bf16x8*)(ub + (16 * tg + fr) * 72 + 32 + 8 * g);
;   const u16* WGT = (const u16*)(p.ws + OFF_WGT);
;   float* exw = ex + tg * 16 * 65;
;   float av[2][16], bv[2][16];
; #pragma unroll
;   for (int d = 0; d < 2; ++d) {
;     float pre[2][16];
; #pragma unroll
;     for (int mat = 0; mat < 2; ++mat) {
;       const u16* wb = WGT + (size_t)((((l * 2 + d) * 2 + mat) * 4 + n) * 64) * 64 + 8 * g;
;       f32x4 acc[4];
; #pragma unroll
;       for (int nt = 0; nt < 4; ++nt) {
;         const bf16x8 B0 = *(const bf16x8*)(wb + (16 * nt + fr) * 64), B1 = *(const bf16x8*)(wb + (16 * nt + fr) * 64 + 32);
;         f32x4 z = {0.f, 0.f, 0.f, 0.f};
;         z = mfma16(A0, B0, z); z = mfma16(A1, B1, z); acc[nt] = z;
.LBB0_1555:
	s_or_b64 exec, exec, s[6:7]
	s_bitset1_b32 s1, 8
	s_lshl_b32 s5, s76, 1
	v_lshlrev_b32_e32 v0, 3, v18
	s_add_u32 s6, s36, s5
	v_and_b32_e32 v8, 0x78, v0
	s_addc_u32 s7, s37, 0
	v_lshlrev_b32_e32 v212, 1, v8
	v_ashrrev_i32_e32 v9, 4, v76
	v_lshl_add_u64 v[4:5], s[6:7], 0, v[212:213]
	v_add_u32_e32 v0, s1, v9
	v_mad_i64_i32 v[0:1], s[6:7], v0, s87, v[4:5]
	s_waitcnt lgkmcnt(0)
	s_barrier
	global_load_dwordx4 v[0:3], v[0:1], off
	v_ashrrev_i32_e32 v11, 4, v19
	v_add_u32_e32 v6, s1, v11
	v_mad_i64_i32 v[4:5], s[6:7], v6, s87, v[4:5]
	global_load_dwordx4 v[4:7], v[4:5], off
	s_movk_i32 s1, 0x244
	v_mul_lo_u32 v9, v9, s1
	v_lshlrev_b32_e32 v8, 2, v8
	v_add3_u32 v9, 0, v9, v8
	v_lshlrev_b32_e32 v61, 4, v56
	v_and_b32_e32 v10, 15, v18
	v_readlane_b32 s6, v252, 63
	v_and_b32_e32 v212, 48, v57
	v_readlane_b32 s7, v253, 0
	s_lshl_b32 s0, s0, 13
	s_or_b32 s90, s0, s89
	v_lshlrev_b32_e32 v107, 6, v10
	v_mov_b32_e32 v31, v213
	v_mov_b32_e32 v33, v213
	v_lshrrev_b32_e32 v75, 4, v57
	s_movk_i32 s0, 0x410
	v_or_b32_e32 v35, 0x400, v107
	v_or_b32_e32 v36, s88, v55
	v_mov_b32_e32 v37, v213
	v_readlane_b32 s8, v252, 30
	v_readlane_b32 s9, v252, 31
	v_readlane_b32 s10, v252, 32
	v_readlane_b32 s11, v252, 33
	v_readlane_b32 s12, v252, 34
	v_readlane_b32 s13, v252, 35
	v_readlane_b32 s14, v252, 36
	v_readlane_b32 s15, v252, 37
	v_readlane_b32 s16, v252, 38
	v_readlane_b32 s17, v252, 39
	v_readlane_b32 s18, v252, 40
	v_readlane_b32 s19, v252, 41
	v_readlane_b32 s20, v252, 42
	v_readlane_b32 s21, v252, 43
	v_readlane_b32 s22, v252, 44
	v_readlane_b32 s23, v252, 45
	s_waitcnt vmcnt(1)
	v_and_b32_e32 v12, 0xffff0000, v0
	v_lshlrev_b32_e32 v0, 16, v0
	ds_write2_b32 v9, v0, v12 offset0:8 offset1:9
	v_and_b32_e32 v0, 0xffff0000, v1
	v_lshlrev_b32_e32 v1, 16, v1
	ds_write2_b32 v9, v1, v0 offset0:10 offset1:11
	v_and_b32_e32 v0, 0xffff0000, v2
	v_lshlrev_b32_e32 v1, 16, v2
	ds_write2_b32 v9, v1, v0 offset0:12 offset1:13
	v_and_b32_e32 v0, 0xffff0000, v3
	v_lshlrev_b32_e32 v1, 16, v3
	ds_write2_b32 v9, v1, v0 offset0:14 offset1:15
	v_mul_lo_u32 v0, v11, s1
	v_add3_u32 v0, 0, v0, v8
	s_waitcnt vmcnt(0)
	v_and_b32_e32 v1, 0xffff0000, v4
	v_lshlrev_b32_e32 v2, 16, v4
	ds_write2_b32 v0, v2, v1 offset0:8 offset1:9
	v_and_b32_e32 v1, 0xffff0000, v5
	v_lshlrev_b32_e32 v2, 16, v5
	ds_write2_b32 v0, v2, v1 offset0:10 offset1:11
	v_and_b32_e32 v1, 0xffff0000, v6
	v_lshlrev_b32_e32 v2, 16, v6
	ds_write2_b32 v0, v2, v1 offset0:12 offset1:13
	v_and_b32_e32 v1, 0xffff0000, v7
	v_lshlrev_b32_e32 v2, 16, v7
	ds_write2_b32 v0, v2, v1 offset0:14 offset1:15
	v_or_b32_e32 v0, v61, v10
	s_movk_i32 s1, 0x90
	v_mul_lo_u32 v0, v0, s1
	s_movk_i32 s1, 0x1040
	v_mul_lo_u32 v8, v56, s1
	v_add_u32_e32 v11, 0, v8
	v_lshl_add_u64 v[8:9], s[6:7], 0, v[212:213]
	v_add3_u32 v0, 0, v0, v212
	v_lshl_add_u64 v[28:29], v[8:9], 0, s[90:91]
	v_lshlrev_b32_e32 v212, 7, v10
	v_lshl_add_u64 v[16:17], v[28:29], 0, v[212:213]
	ds_read_b128 v[4:7], v0 offset:37120
	ds_read_b128 v[0:3], v0 offset:37184
	v_lshl_add_u32 v90, v10, 2, v11
	v_lshl_add_u32 v34, v57, 2, v11
	s_mov_b64 s[30:31], 0x1000
	v_lshl_add_u64 v[214:215], v[16:17], 0, s[30:31]
	s_mov_b64 s[30:31], 0x9000
	v_lshl_add_u64 v[216:217], v[16:17], 0, s[30:31]
	s_mov_b64 s[30:31], 0x11000
	v_lshl_add_u64 v[220:221], v[16:17], 0, s[30:31]
	s_mov_b64 s[30:31], 0x19000
	v_lshl_add_u64 v[222:223], v[16:17], 0, s[30:31]
	global_load_dwordx4 v[152:155], v[214:215], off offset:-4096
	global_load_dwordx4 v[156:159], v[214:215], off offset:-4032
	global_load_dwordx4 v[160:163], v[214:215], off offset:-2048
	global_load_dwordx4 v[164:167], v[214:215], off offset:-1984
	global_load_dwordx4 v[168:171], v[214:215], off
	global_load_dwordx4 v[172:175], v[214:215], off offset:64
	global_load_dwordx4 v[176:179], v[214:215], off offset:2048
	global_load_dwordx4 v[180:183], v[214:215], off offset:2112
	global_load_dwordx4 v[184:187], v[216:217], off offset:-4096
	global_load_dwordx4 v[188:191], v[216:217], off offset:-4032
	global_load_dwordx4 v[192:195], v[216:217], off offset:-2048
	global_load_dwordx4 v[196:199], v[216:217], off offset:-1984
	global_load_dwordx4 v[200:203], v[216:217], off
	global_load_dwordx4 v[204:207], v[216:217], off offset:64
	global_load_dwordx4 v[208:211], v[216:217], off offset:2048
	global_load_dwordx4 v[144:147], v[216:217], off offset:2112
	s_nop 0
	v_add_u32_e32 v97, 0xd800, v34
	v_add_u32_e32 v98, 0xda00, v34
	v_add_u32_e32 v99, 0xdc00, v34
	v_add_u32_e32 v100, 0xde00, v34
	v_add_u32_e32 v102, 0xe000, v34
	v_add_u32_e32 v103, 0xe200, v34
	v_add_u32_e32 v104, 0xe400, v34
	v_add_u32_e32 v105, 0xe600, v34
	v_lshlrev_b32_e32 v34, 1, v35
	v_mov_b32_e32 v35, v213
	s_waitcnt vmcnt(15) lgkmcnt(1)
	v_mfma_f32_16x16x32_bf16 v[8:11], v[4:7], v[152:155], 0
	s_waitcnt vmcnt(14) lgkmcnt(0)
	v_mfma_f32_16x16x32_bf16 v[8:11], v[0:3], v[156:159], v[8:11]
	s_nop 0
	s_nop 0
	s_nop 0
	s_waitcnt vmcnt(13)
	v_mfma_f32_16x16x32_bf16 v[12:15], v[4:7], v[160:163], 0
	s_waitcnt vmcnt(12)
	v_mfma_f32_16x16x32_bf16 v[12:15], v[0:3], v[164:167], v[12:15]
	v_or_b32_e32 v16, 0x800, v107
	v_lshlrev_b32_e32 v30, 1, v16
	v_lshl_add_u64 v[20:21], v[28:29], 0, v[30:31]
	s_nop 0
	s_nop 0
	s_nop 0
	s_waitcnt vmcnt(11)
	v_mfma_f32_16x16x32_bf16 v[16:19], v[4:7], v[168:171], 0
	s_waitcnt vmcnt(10)
	v_mfma_f32_16x16x32_bf16 v[16:19], v[0:3], v[172:175], v[16:19]
	v_or_b32_e32 v20, 0xc00, v107
	v_lshlrev_b32_e32 v32, 1, v20
	v_lshl_add_u64 v[24:25], v[28:29], 0, v[32:33]
	s_nop 0
	s_nop 0
	s_nop 0
	s_waitcnt lgkmcnt(0)
	s_waitcnt vmcnt(9)
	v_mfma_f32_16x16x32_bf16 v[20:23], v[4:7], v[176:179], 0
	s_waitcnt vmcnt(8)
; DEVI f32x4 mfma16(bf16x8 a, bf16x8 b, f32x4 c) { return __builtin_amdgcn_mfma_f32_16x16x32_bf16(a, b, c, 0, 0, 0); }
; DEVI void lru_item(const Params& p, int l, int item, int pass) {
;     ...
;       const u16* wb = WGT + (size_t)((((l * 2 + d) * 2 + mat) * 4 + n) * 64) * 64 + 8 * g;
;       f32x4 acc[4];
; #pragma unroll
;       for (int nt = 0; nt < 4; ++nt) {
;         const bf16x8 B0 = *(const bf16x8*)(wb + (16 * nt + fr) * 64), B1 = *(const bf16x8*)(wb + (16 * nt + fr) * 64 + 32);
;         f32x4 z = {0.f, 0.f, 0.f, 0.f};
;         z = mfma16(A0, B0, z); z = mfma16(A1, B1, z); acc[nt] = z;
;       }
;       asm volatile("s_waitcnt lgkmcnt(0)" ::: "memory");
; #pragma unroll
;       for (int nt = 0; nt < 4; ++nt)
; #pragma unroll
;         for (int j = 0; j < 4; ++j) exw[(4 * g + j) * 65 + 16 * nt + fr] = acc[nt][j];
;       asm volatile("s_waitcnt lgkmcnt(0)" ::: "memory");
; #pragma unroll
;       for (int tt = 0; tt < 16; ++tt) pre[mat][tt] = exw[tt * 65 + lane];
;     }
;     const float ba = p.in[14][(l * 2 + d) * 256 + c], bx = p.in[16][(l * 2 + d) * 256 + c];
;     const float lam = p.in[17][(l * 2 + d) * 256 + c];
;     const float exl = __expf(-lam); const float sp = exl < 0.03f ? exl * (1.f - exl * (0.5f - exl * (0.33333334f - 0.25f * exl))) : __logf(1.f + exl);
	v_mfma_f32_16x16x32_bf16 v[20:23], v[0:3], v[180:183], v[20:23]
	v_mad_u32_u24 v24, v75, s0, v90
	v_add_u32_e32 v26, 0xd800, v24
	v_add_u32_e32 v27, 0xdc00, v24
	s_mov_b64 s[0:1], 0x8000
	ds_write2_b32 v26, v8, v12 offset0:64 offset1:80
	ds_write2_b32 v26, v9, v13 offset0:129 offset1:145
	ds_write2_b32 v26, v10, v14 offset0:194 offset1:210
	ds_write2_b32 v27, v11, v15 offset0:3 offset1:19
	ds_write2_b32 v26, v16, v20 offset0:96 offset1:112
	ds_write2_b32 v26, v17, v21 offset0:161 offset1:177
	ds_write2_b32 v26, v18, v22 offset0:226 offset1:242
	ds_write2_b32 v27, v19, v23 offset0:35 offset1:51
	v_lshl_add_u64 v[18:19], v[28:29], 0, s[0:1]
	s_waitcnt lgkmcnt(0)
	v_lshl_add_u64 v[22:23], v[18:19], 0, v[212:213]
	ds_read2_b32 v[50:51], v97 offset0:64 offset1:129
	ds_read2_b32 v[46:47], v98 offset0:66 offset1:131
	ds_read2_b32 v[42:43], v99 offset0:68 offset1:133
	ds_read2_b32 v[24:25], v100 offset0:70 offset1:135
	ds_read2_b32 v[20:21], v102 offset0:72 offset1:137
	ds_read2_b32 v[16:17], v103 offset0:74 offset1:139
	ds_read2_b32 v[10:11], v104 offset0:76 offset1:141
	ds_read2_b32 v[8:9], v105 offset0:78 offset1:143
	s_nop 0
	s_nop 0
	v_lshl_add_u64 v[22:23], v[18:19], 0, v[34:35]
	s_mov_b32 s0, 0x3cf5c28f
	s_waitcnt vmcnt(7)
	v_mfma_f32_16x16x32_bf16 v[12:15], v[4:7], v[184:187], 0
	s_waitcnt vmcnt(6)
	v_mfma_f32_16x16x32_bf16 v[12:15], v[0:3], v[188:191], v[12:15]
	s_nop 0
	s_nop 0
	v_lshl_add_u64 v[22:23], v[18:19], 0, v[30:31]
	v_lshl_add_u64 v[18:19], v[18:19], 0, v[32:33]
	s_waitcnt vmcnt(5)
	v_mfma_f32_16x16x32_bf16 v[38:41], v[4:7], v[192:195], 0
	s_waitcnt vmcnt(4)
	v_mfma_f32_16x16x32_bf16 v[38:41], v[0:3], v[196:199], v[38:41]
	s_nop 0
	s_nop 0
	s_waitcnt vmcnt(3)
	v_mfma_f32_16x16x32_bf16 v[78:81], v[4:7], v[200:203], 0
	s_waitcnt vmcnt(2)
	v_mfma_f32_16x16x32_bf16 v[78:81], v[0:3], v[204:207], v[78:81]
	s_nop 0
	s_nop 0
	s_waitcnt lgkmcnt(0)
	s_waitcnt vmcnt(1)
	v_mfma_f32_16x16x32_bf16 v[82:85], v[4:7], v[208:211], 0
	s_waitcnt vmcnt(0)
	v_mfma_f32_16x16x32_bf16 v[82:85], v[0:3], v[144:147], v[82:85]
	global_load_dwordx4 v[152:155], v[220:221], off offset:-4096
	global_load_dwordx4 v[156:159], v[220:221], off offset:-4032
	global_load_dwordx4 v[160:163], v[220:221], off offset:-2048
	global_load_dwordx4 v[164:167], v[220:221], off offset:-1984
	global_load_dwordx4 v[168:171], v[220:221], off
	global_load_dwordx4 v[172:175], v[220:221], off offset:64
	global_load_dwordx4 v[176:179], v[220:221], off offset:2048
	global_load_dwordx4 v[180:183], v[220:221], off offset:2112
	global_load_dwordx4 v[184:187], v[222:223], off offset:-4096
	global_load_dwordx4 v[188:191], v[222:223], off offset:-4032
	global_load_dwordx4 v[192:195], v[222:223], off offset:-2048
	global_load_dwordx4 v[196:199], v[222:223], off offset:-1984
	global_load_dwordx4 v[200:203], v[222:223], off
	global_load_dwordx4 v[204:207], v[222:223], off offset:64
	global_load_dwordx4 v[208:211], v[222:223], off offset:2048
	global_load_dwordx4 v[144:147], v[222:223], off offset:2112
	ds_write2_b32 v26, v12, v38 offset0:64 offset1:80
	ds_write2_b32 v26, v13, v39 offset0:129 offset1:145
	ds_write2_b32 v26, v14, v40 offset0:194 offset1:210
	ds_write2_b32 v27, v15, v41 offset0:3 offset1:19
	s_nop 3
	ds_write2_b32 v26, v78, v82 offset0:96 offset1:112
	ds_write2_b32 v26, v79, v83 offset0:161 offset1:177
	ds_write2_b32 v26, v80, v84 offset0:226 offset1:242
	ds_write2_b32 v27, v81, v85 offset0:35 offset1:51
	v_lshlrev_b64 v[40:41], 2, v[36:37]
	v_lshl_add_u64 v[36:37], s[20:21], 0, v[40:41]
	v_readlane_b32 s8, v252, 46
	v_readlane_b32 s9, v252, 47
	v_readlane_b32 s10, v252, 48
	v_readlane_b32 s11, v252, 49
	s_waitcnt lgkmcnt(0)
	v_lshl_add_u64 v[38:39], s[8:9], 0, v[40:41]
	ds_read2_b32 v[52:53], v97 offset0:64 offset1:129
	ds_read2_b32 v[48:49], v98 offset0:66 offset1:131
	ds_read2_b32 v[44:45], v99 offset0:68 offset1:133
	ds_read2_b32 v[26:27], v100 offset0:70 offset1:135
	ds_read2_b32 v[22:23], v102 offset0:72 offset1:137
	ds_read2_b32 v[18:19], v103 offset0:74 offset1:139
	ds_read2_b32 v[14:15], v104 offset0:76 offset1:141
	ds_read2_b32 v[12:13], v105 offset0:78 offset1:143
	v_lshl_add_u64 v[40:41], s[10:11], 0, v[40:41]
	global_load_dword v35, v[40:41], off
	global_load_dword v31, v[36:37], off
	global_load_dword v33, v[38:39], off
	v_readlane_b32 s12, v252, 50
	v_readlane_b32 s13, v252, 51
	v_readlane_b32 s14, v252, 52
	v_readlane_b32 s15, v252, 53
	v_readlane_b32 s16, v252, 54
	v_readlane_b32 s17, v252, 55
	v_readlane_b32 s18, v252, 56
	v_readlane_b32 s19, v252, 57
	v_readlane_b32 s20, v252, 58
	v_readlane_b32 s21, v252, 59
	v_readlane_b32 s22, v252, 60
	v_readlane_b32 s23, v252, 61
	s_waitcnt vmcnt(2)
	v_mul_f32_e32 v35, 0xbfb8aa3b, v35
	v_exp_f32_e32 v77, v35
	s_nop 0
	v_cmp_ngt_f32_e32 vcc, s0, v77
	s_and_saveexec_b64 s[0:1], vcc
	s_xor_b64 s[8:9], exec, s[0:1]
	s_cbranch_execz .LBB0_1557
	v_add_f32_e32 v35, 1.0, v77
	v_cmp_gt_f32_e32 vcc, s63, v35
	s_mov_b32 s0, 0x3f317217
	s_nop 0
	v_cndmask_b32_e64 v77, 0, 32, vcc
	v_ldexp_f32 v35, v35, v77
	v_log_f32_e32 v35, v35
	s_nop 0
	v_mul_f32_e32 v77, 0x3f317217, v35
	v_fma_f32 v77, v35, s0, -v77
	v_fmac_f32_e32 v77, 0x3377d1cf, v35
	s_mov_b32 s0, 0x7f800000
	v_fmac_f32_e32 v77, 0x3f317217, v35
	v_cmp_lt_f32_e64 s[6:7], |v35|, s0
	s_nop 1
	v_cndmask_b32_e64 v35, v35, v77, s[6:7]
	v_cndmask_b32_e32 v77, 0, v225, vcc
	v_sub_f32_e32 v35, v35, v77
; DEVI float sigmoidf_(float x) { return __builtin_amdgcn_rcpf(1.f + __expf(-x)); }
; DEVI void lru_item(const Params& p, int l, int item, int pass) {
;     ...
;     const float exl = __expf(-lam); const float sp = exl < 0.03f ? exl * (1.f - exl * (0.5f - exl * (0.33333334f - 0.25f * exl))) : __logf(1.f + exl);
;     float Ap = 1.f, Bp = 0.f;
; #pragma unroll
;     for (int q = 0; q < 16; ++q) {
;       const int tt = d == 0 ? q : 15 - q;
;       const float r = sigmoidf_(pre[0][tt] + ba), ig = sigmoidf_(pre[1][tt] + bx);
;       const float la = -8.f * r * sp;
;       const float a = __expf(la);
;       const float om = fmaxf(1.f - a * a, 0.f);
;       const float bb = sqrtf(om) * (ig * uo[tt]);
;       av[d][tt] = a; bv[d][tt] = bb;
;       Bp = a * Bp + bb; Ap *= a;
.LBB0_1557:
	s_andn2_saveexec_b64 s[6:7], s[8:9]
	v_mov_b32_e32 v35, 0x3eaaaaab
	v_fmamk_f32 v35, v77, 0xbe800000, v35
	v_fma_f32 v35, -v77, v35, 0.5
	v_fma_f32 v35, -v77, v35, 1.0
	v_mul_f32_e32 v35, v77, v35
	s_or_b64 exec, exec, s[6:7]
	s_waitcnt vmcnt(1) lgkmcnt(14)
	v_add_f32_e32 v50, v50, v31
	v_mul_f32_e32 v50, 0xbfb8aa3b, v50
	v_exp_f32_e32 v50, v50
	s_waitcnt vmcnt(0) lgkmcnt(7)
	v_add_f32_e32 v52, v52, v33
	v_mul_f32_e32 v52, 0xbfb8aa3b, v52
	v_exp_f32_e32 v52, v52
	v_add_f32_e32 v50, 1.0, v50
	v_rcp_f32_e32 v50, v50
	v_mul_u32_u24_e32 v108, 0x410, v75
	v_add_f32_e32 v52, 1.0, v52
	v_rcp_f32_e32 v75, v52
	v_mul_f32_e32 v50, 0xc1000000, v50
	v_mul_f32_e32 v50, v50, v35
	v_mul_f32_e32 v50, 0x3fb8aa3b, v50
	v_exp_f32_e32 v52, v50
	v_add_f32_e32 v51, v51, v31
	v_mul_f32_e32 v51, 0xbfb8aa3b, v51
	v_exp_f32_e32 v51, v51
	v_fma_f32 v50, -v52, v52, 1.0
	v_max_f32_e32 v50, 0, v50
	v_cmp_gt_f32_e32 vcc, s92, v50
	v_mul_f32_e32 v77, 0x4f800000, v50
	v_add_f32_e32 v51, 1.0, v51
	v_cndmask_b32_e32 v50, v50, v77, vcc
	v_sqrt_f32_e32 v77, v50
	v_rcp_f32_e32 v51, v51
	v_add_f32_e32 v53, v53, v33
	v_mul_f32_e32 v53, 0xbfb8aa3b, v53
	v_add_u32_e32 v78, -1, v77
	v_fma_f32 v79, -v78, v77, v50
	v_cmp_ge_f32_e64 s[6:7], 0, v79
	v_add_u32_e32 v79, 1, v77
	v_exp_f32_e32 v53, v53
	v_cndmask_b32_e64 v78, v77, v78, s[6:7]
	v_fma_f32 v77, -v79, v77, v50
	v_cmp_lt_f32_e64 s[6:7], 0, v77
	v_mul_f32_e32 v51, 0xc1000000, v51
	v_mul_f32_e32 v51, v51, v35
	v_cndmask_b32_e64 v77, v78, v79, s[6:7]
	v_mul_f32_e32 v78, 0x37800000, v77
	v_cndmask_b32_e32 v77, v77, v78, vcc
	v_cmp_class_f32_e32 vcc, v50, v235
	v_add_f32_e32 v53, 1.0, v53
	v_mul_f32_e32 v51, 0x3fb8aa3b, v51
	v_cndmask_b32_e32 v50, v77, v50, vcc
	v_rcp_f32_e32 v77, v53
	v_exp_f32_e32 v53, v51
	v_add_f32_e32 v46, v46, v31
	v_mul_f32_e32 v46, 0xbfb8aa3b, v46
	v_exp_f32_e32 v46, v46
	v_fma_f32 v51, -v53, v53, 1.0
	v_max_f32_e32 v51, 0, v51
	v_cmp_gt_f32_e32 vcc, s92, v51
	v_mul_f32_e32 v78, 0x4f800000, v51
	v_add_f32_e32 v46, 1.0, v46
	v_cndmask_b32_e32 v51, v51, v78, vcc
	v_sqrt_f32_e32 v78, v51
	v_rcp_f32_e32 v46, v46
	s_waitcnt lgkmcnt(6)
	v_add_f32_e32 v48, v48, v33
	v_mul_f32_e32 v48, 0xbfb8aa3b, v48
	v_add_u32_e32 v79, -1, v78
	v_fma_f32 v80, -v79, v78, v51
	v_cmp_ge_f32_e64 s[6:7], 0, v80
	v_add_u32_e32 v80, 1, v78
	v_exp_f32_e32 v48, v48
	v_cndmask_b32_e64 v79, v78, v79, s[6:7]
	v_fma_f32 v78, -v80, v78, v51
	v_cmp_lt_f32_e64 s[6:7], 0, v78
	v_mul_f32_e32 v46, 0xc1000000, v46
	v_mul_f32_e32 v46, v46, v35
	v_cndmask_b32_e64 v78, v79, v80, s[6:7]
	v_mul_f32_e32 v79, 0x37800000, v78
	v_cndmask_b32_e32 v78, v78, v79, vcc
	v_cmp_class_f32_e32 vcc, v51, v235
	v_add_f32_e32 v48, 1.0, v48
	v_mul_f32_e32 v46, 0x3fb8aa3b, v46
	v_cndmask_b32_e32 v51, v78, v51, vcc
	v_rcp_f32_e32 v78, v48
	v_exp_f32_e32 v48, v46
	v_add_f32_e32 v47, v47, v31
	v_mul_f32_e32 v47, 0xbfb8aa3b, v47
	v_exp_f32_e32 v47, v47
	v_fma_f32 v46, -v48, v48, 1.0
	v_max_f32_e32 v46, 0, v46
	v_cmp_gt_f32_e32 vcc, s92, v46
	v_mul_f32_e32 v79, 0x4f800000, v46
	v_add_f32_e32 v47, 1.0, v47
	v_cndmask_b32_e32 v46, v46, v79, vcc
	v_sqrt_f32_e32 v79, v46
	v_rcp_f32_e32 v47, v47
	v_add_f32_e32 v49, v49, v33
	v_mul_f32_e32 v49, 0xbfb8aa3b, v49
	v_add_u32_e32 v80, -1, v79
	v_fma_f32 v81, -v80, v79, v46
	v_cmp_ge_f32_e64 s[6:7], 0, v81
	v_add_u32_e32 v81, 1, v79
	v_exp_f32_e32 v49, v49
	v_cndmask_b32_e64 v80, v79, v80, s[6:7]
	v_fma_f32 v79, -v81, v79, v46
	v_cmp_lt_f32_e64 s[6:7], 0, v79
	v_mul_f32_e32 v47, 0xc1000000, v47
	v_mul_f32_e32 v47, v47, v35
	v_cndmask_b32_e64 v79, v80, v81, s[6:7]
	v_mul_f32_e32 v80, 0x37800000, v79
	v_cndmask_b32_e32 v79, v79, v80, vcc
	v_cmp_class_f32_e32 vcc, v46, v235
	v_mul_f32_e32 v78, v60, v78
	v_add_f32_e32 v49, 1.0, v49
	v_cndmask_b32_e32 v46, v79, v46, vcc
	v_mul_f32_e32 v47, 0x3fb8aa3b, v47
	v_mul_f32_e32 v46, v78, v46
	v_rcp_f32_e32 v78, v49
	v_exp_f32_e32 v49, v47
	v_add_f32_e32 v42, v42, v31
	v_mul_f32_e32 v42, 0xbfb8aa3b, v42
	v_exp_f32_e32 v42, v42
	v_fma_f32 v47, -v49, v49, 1.0
	v_max_f32_e32 v47, 0, v47
	v_cmp_gt_f32_e32 vcc, s92, v47
	v_mul_f32_e32 v79, 0x4f800000, v47
	v_add_f32_e32 v42, 1.0, v42
	v_cndmask_b32_e32 v47, v47, v79, vcc
	v_sqrt_f32_e32 v79, v47
	v_rcp_f32_e32 v42, v42
	v_mul_f32_e32 v75, v58, v75
	v_mul_f32_e32 v50, v75, v50
	v_add_u32_e32 v80, -1, v79
	v_fma_f32 v81, -v80, v79, v47
	v_cmp_ge_f32_e64 s[6:7], 0, v81
	v_add_u32_e32 v81, 1, v79
	v_mul_f32_e32 v77, v59, v77
	v_cndmask_b32_e64 v80, v79, v80, s[6:7]
	v_fma_f32 v79, -v81, v79, v47
	v_cmp_lt_f32_e64 s[6:7], 0, v79
	v_fma_f32 v75, 0, v52, v50
	v_mul_f32_e32 v51, v77, v51
	v_cndmask_b32_e64 v79, v80, v81, s[6:7]
	v_mul_f32_e32 v80, 0x37800000, v79
	v_cndmask_b32_e32 v79, v79, v80, vcc
	v_cmp_class_f32_e32 vcc, v47, v235
	v_mul_f32_e32 v42, 0xc1000000, v42
	v_fma_f32 v75, v53, v75, v51
	v_cndmask_b32_e32 v47, v79, v47, vcc
	v_mul_f32_e32 v78, v62, v78
	v_mul_f32_e32 v42, v42, v35
	v_fma_f32 v75, v48, v75, v46
	v_mul_f32_e32 v47, v78, v47
	v_mul_f32_e32 v42, 0x3fb8aa3b, v42
	v_fma_f32 v78, v49, v75, v47
	v_exp_f32_e32 v75, v42
	v_add_f32_e32 v43, v43, v31
	s_waitcnt lgkmcnt(5)
; DEVI float sigmoidf_(float x) { return __builtin_amdgcn_rcpf(1.f + __expf(-x)); }
; DEVI void lru_item(const Params& p, int l, int item, int pass) {
;     ...
;     for (int q = 0; q < 16; ++q) {
;       const int tt = d == 0 ? q : 15 - q;
;       const float r = sigmoidf_(pre[0][tt] + ba), ig = sigmoidf_(pre[1][tt] + bx);
;       const float la = -8.f * r * sp;
;       const float a = __expf(la);
;       const float om = fmaxf(1.f - a * a, 0.f);
;       const float bb = sqrtf(om) * (ig * uo[tt]);
;       av[d][tt] = a; bv[d][tt] = bb;
;       Bp = a * Bp + bb; Ap *= a;
	v_add_f32_e32 v44, v44, v33
	v_mul_f32_e32 v43, 0xbfb8aa3b, v43
	v_fma_f32 v42, -v75, v75, 1.0
	v_max_f32_e32 v42, 0, v42
	v_cmp_gt_f32_e32 vcc, s92, v42
	v_mul_f32_e32 v79, 0x4f800000, v42
	v_mul_f32_e32 v44, 0xbfb8aa3b, v44
	v_cndmask_b32_e32 v42, v42, v79, vcc
	v_sqrt_f32_e32 v79, v42
	v_exp_f32_e32 v43, v43
	v_exp_f32_e32 v44, v44
	v_mul_f32_e32 v77, v52, v53
	v_add_u32_e32 v80, -1, v79
	v_fma_f32 v81, -v80, v79, v42
	v_cmp_ge_f32_e64 s[6:7], 0, v81
	v_add_u32_e32 v81, 1, v79
	v_add_f32_e32 v43, 1.0, v43
	v_add_f32_e32 v44, 1.0, v44
	v_cndmask_b32_e64 v80, v79, v80, s[6:7]
	v_fma_f32 v79, -v81, v79, v42
	v_rcp_f32_e32 v43, v43
	v_rcp_f32_e32 v44, v44
	v_cmp_lt_f32_e64 s[6:7], 0, v79
	v_mul_f32_e32 v77, v48, v77
	v_mul_f32_e32 v43, 0xc1000000, v43
	v_cndmask_b32_e64 v79, v80, v81, s[6:7]
	v_mul_f32_e32 v80, 0x37800000, v79
	v_cndmask_b32_e32 v79, v79, v80, vcc
	v_cmp_class_f32_e32 vcc, v42, v235
	v_mul_f32_e32 v44, v63, v44
	v_mul_f32_e32 v43, v43, v35
	v_cndmask_b32_e32 v42, v79, v42, vcc
	v_mul_f32_e32 v77, v49, v77
	v_mul_f32_e32 v44, v44, v42
	v_mul_f32_e32 v43, 0x3fb8aa3b, v43
	v_fma_f32 v42, v75, v78, v44
	v_mul_f32_e32 v78, v75, v77
	v_exp_f32_e32 v77, v43
	v_add_f32_e32 v24, v24, v31
	v_mul_f32_e32 v24, 0xbfb8aa3b, v24
	v_exp_f32_e32 v24, v24
	v_fma_f32 v43, -v77, v77, 1.0
	v_max_f32_e32 v43, 0, v43
	v_cmp_gt_f32_e32 vcc, s92, v43
	v_mul_f32_e32 v79, 0x4f800000, v43
	v_add_f32_e32 v24, 1.0, v24
	v_cndmask_b32_e32 v43, v43, v79, vcc
	v_sqrt_f32_e32 v79, v43
	v_rcp_f32_e32 v24, v24
	v_add_f32_e32 v45, v45, v33
	v_mul_f32_e32 v45, 0xbfb8aa3b, v45
	v_add_u32_e32 v80, -1, v79
	v_fma_f32 v81, -v80, v79, v43
	v_cmp_ge_f32_e64 s[6:7], 0, v81
	v_add_u32_e32 v81, 1, v79
	v_exp_f32_e32 v45, v45
	v_cndmask_b32_e64 v80, v79, v80, s[6:7]
	v_fma_f32 v79, -v81, v79, v43
	v_cmp_lt_f32_e64 s[6:7], 0, v79
	v_mul_f32_e32 v24, 0xc1000000, v24
	v_mul_f32_e32 v24, v24, v35
	v_cndmask_b32_e64 v79, v80, v81, s[6:7]
	v_mul_f32_e32 v80, 0x37800000, v79
	v_cndmask_b32_e32 v79, v79, v80, vcc
	v_cmp_class_f32_e32 vcc, v43, v235
	v_mul_f32_e32 v24, 0x3fb8aa3b, v24
	v_add_f32_e32 v45, 1.0, v45
	v_cndmask_b32_e32 v43, v79, v43, vcc
	v_exp_f32_e32 v79, v24
	v_rcp_f32_e32 v45, v45
	v_add_f32_e32 v25, v25, v31
	v_mul_f32_e32 v25, 0xbfb8aa3b, v25
	v_fma_f32 v24, -v79, v79, 1.0
	v_mul_f32_e32 v45, v64, v45
	v_max_f32_e32 v24, 0, v24
	v_exp_f32_e32 v25, v25
	v_mul_f32_e32 v45, v45, v43
	v_mul_f32_e32 v43, v77, v78
	v_cmp_gt_f32_e32 vcc, s92, v24
	v_mul_f32_e32 v78, 0x4f800000, v24
	v_add_f32_e32 v25, 1.0, v25
	v_cndmask_b32_e32 v24, v24, v78, vcc
	v_sqrt_f32_e32 v78, v24
	s_waitcnt lgkmcnt(4)
	v_add_f32_e32 v26, v26, v33
	v_rcp_f32_e32 v25, v25
	v_mul_f32_e32 v26, 0xbfb8aa3b, v26
	v_exp_f32_e32 v26, v26
	v_add_u32_e32 v80, -1, v78
	v_fma_f32 v81, -v80, v78, v24
	v_cmp_ge_f32_e64 s[6:7], 0, v81
	v_add_u32_e32 v81, 1, v78
	v_mul_f32_e32 v25, 0xc1000000, v25
	v_cndmask_b32_e64 v80, v78, v80, s[6:7]
	v_fma_f32 v78, -v81, v78, v24
	v_mul_f32_e32 v25, v25, v35
	v_add_f32_e32 v26, 1.0, v26
	v_cmp_lt_f32_e64 s[6:7], 0, v78
	v_mul_f32_e32 v25, 0x3fb8aa3b, v25
	v_rcp_f32_e32 v26, v26
	v_cndmask_b32_e64 v78, v80, v81, s[6:7]
	v_exp_f32_e32 v81, v25
	v_add_f32_e32 v20, v20, v31
	v_mul_f32_e32 v80, 0x37800000, v78
	v_mul_f32_e32 v20, 0xbfb8aa3b, v20
	v_cndmask_b32_e32 v78, v78, v80, vcc
	v_cmp_class_f32_e32 vcc, v24, v235
	v_exp_f32_e32 v20, v20
	v_mul_f32_e32 v26, v65, v26
	v_cndmask_b32_e32 v24, v78, v24, vcc
	v_fma_f32 v25, -v81, v81, 1.0
	v_fma_f32 v42, v77, v42, v45
	v_mul_f32_e32 v78, v26, v24
	v_max_f32_e32 v25, 0, v25
	v_fma_f32 v24, v79, v42, v78
	v_cmp_gt_f32_e32 vcc, s92, v25
	v_mul_f32_e32 v42, 0x4f800000, v25
	v_add_f32_e32 v20, 1.0, v20
	v_cndmask_b32_e32 v25, v25, v42, vcc
	v_sqrt_f32_e32 v42, v25
	v_rcp_f32_e32 v20, v20
	v_add_f32_e32 v27, v27, v33
	v_mul_f32_e32 v27, 0xbfb8aa3b, v27
	v_exp_f32_e32 v27, v27
	v_mul_f32_e32 v26, v79, v43
	v_add_u32_e32 v43, -1, v42
	v_mul_f32_e32 v20, 0xc1000000, v20
	v_fma_f32 v80, -v43, v42, v25
	v_mul_f32_e32 v20, v20, v35
	v_cmp_ge_f32_e64 s[6:7], 0, v80
	v_add_u32_e32 v80, 1, v42
	v_mul_f32_e32 v20, 0x3fb8aa3b, v20
	v_add_f32_e32 v27, 1.0, v27
	v_cndmask_b32_e64 v43, v42, v43, s[6:7]
	v_fma_f32 v42, -v80, v42, v25
	v_exp_f32_e32 v83, v20
	v_rcp_f32_e32 v27, v27
	v_cmp_lt_f32_e64 s[6:7], 0, v42
	v_add_f32_e32 v21, v21, v31
	v_mul_f32_e32 v21, 0xbfb8aa3b, v21
	v_cndmask_b32_e64 v42, v43, v80, s[6:7]
	v_mul_f32_e32 v43, 0x37800000, v42
	v_cndmask_b32_e32 v42, v42, v43, vcc
	v_cmp_class_f32_e32 vcc, v25, v235
	v_fma_f32 v20, -v83, v83, 1.0
	v_exp_f32_e32 v21, v21
	v_cndmask_b32_e32 v25, v42, v25, vcc
	v_mul_f32_e32 v27, v66, v27
	v_max_f32_e32 v20, 0, v20
	v_mul_f32_e32 v80, v27, v25
	v_mul_f32_e32 v25, v81, v26
	v_cmp_gt_f32_e32 vcc, s92, v20
	v_mul_f32_e32 v26, 0x4f800000, v20
	v_add_f32_e32 v21, 1.0, v21
	v_cndmask_b32_e32 v20, v20, v26, vcc
	v_sqrt_f32_e32 v26, v20
	s_waitcnt lgkmcnt(3)
; DEVI float sigmoidf_(float x) { return __builtin_amdgcn_rcpf(1.f + __expf(-x)); }
; DEVI void lru_item(const Params& p, int l, int item, int pass) {
;     ...
;     for (int q = 0; q < 16; ++q) {
;       const int tt = d == 0 ? q : 15 - q;
;       const float r = sigmoidf_(pre[0][tt] + ba), ig = sigmoidf_(pre[1][tt] + bx);
;       const float la = -8.f * r * sp;
;       const float a = __expf(la);
;       const float om = fmaxf(1.f - a * a, 0.f);
;       const float bb = sqrtf(om) * (ig * uo[tt]);
;       av[d][tt] = a; bv[d][tt] = bb;
;       Bp = a * Bp + bb; Ap *= a;
	v_add_f32_e32 v22, v22, v33
	v_rcp_f32_e32 v21, v21
	v_mul_f32_e32 v22, 0xbfb8aa3b, v22
	v_exp_f32_e32 v22, v22
	v_add_u32_e32 v27, -1, v26
	v_fma_f32 v42, -v27, v26, v20
	v_mul_f32_e32 v21, 0xc1000000, v21
	v_cmp_ge_f32_e64 s[6:7], 0, v42
	v_add_u32_e32 v42, 1, v26
	v_mul_f32_e32 v21, v21, v35
	v_add_f32_e32 v22, 1.0, v22
	v_cndmask_b32_e64 v27, v26, v27, s[6:7]
	v_fma_f32 v26, -v42, v26, v20
	v_mul_f32_e32 v21, 0x3fb8aa3b, v21
	v_rcp_f32_e32 v22, v22
	v_cmp_lt_f32_e64 s[6:7], 0, v26
	v_exp_f32_e32 v85, v21
	v_add_f32_e32 v16, v16, v31
	v_cndmask_b32_e64 v26, v27, v42, s[6:7]
	v_mul_f32_e32 v27, 0x37800000, v26
	v_mul_f32_e32 v16, 0xbfb8aa3b, v16
	v_cndmask_b32_e32 v26, v26, v27, vcc
	v_cmp_class_f32_e32 vcc, v20, v235
	v_exp_f32_e32 v16, v16
	v_mul_f32_e32 v22, v67, v22
	v_cndmask_b32_e32 v20, v26, v20, vcc
	v_fma_f32 v21, -v85, v85, 1.0
	v_fma_f32 v24, v81, v24, v80
	v_mul_f32_e32 v82, v22, v20
	v_max_f32_e32 v21, 0, v21
	v_fma_f32 v20, v83, v24, v82
	v_cmp_gt_f32_e32 vcc, s92, v21
	v_mul_f32_e32 v24, 0x4f800000, v21
	v_add_f32_e32 v16, 1.0, v16
	v_cndmask_b32_e32 v21, v21, v24, vcc
	v_sqrt_f32_e32 v24, v21
	v_rcp_f32_e32 v16, v16
	v_add_f32_e32 v23, v23, v33
	v_mul_f32_e32 v23, 0xbfb8aa3b, v23
	v_exp_f32_e32 v23, v23
	v_mul_f32_e32 v22, v83, v25
	v_add_u32_e32 v25, -1, v24
	v_mul_f32_e32 v16, 0xc1000000, v16
	v_fma_f32 v26, -v25, v24, v21
	v_mul_f32_e32 v16, v16, v35
	v_cmp_ge_f32_e64 s[6:7], 0, v26
	v_add_u32_e32 v26, 1, v24
	v_mul_f32_e32 v16, 0x3fb8aa3b, v16
	v_add_f32_e32 v23, 1.0, v23
	v_cndmask_b32_e64 v25, v24, v25, s[6:7]
	v_fma_f32 v24, -v26, v24, v21
	v_exp_f32_e32 v87, v16
	v_rcp_f32_e32 v23, v23
	v_cmp_lt_f32_e64 s[6:7], 0, v24
	v_add_f32_e32 v17, v17, v31
	v_mul_f32_e32 v17, 0xbfb8aa3b, v17
	v_cndmask_b32_e64 v24, v25, v26, s[6:7]
	v_mul_f32_e32 v25, 0x37800000, v24
	v_cndmask_b32_e32 v24, v24, v25, vcc
	v_cmp_class_f32_e32 vcc, v21, v235
	v_fma_f32 v16, -v87, v87, 1.0
	v_exp_f32_e32 v17, v17
	v_cndmask_b32_e32 v21, v24, v21, vcc
	v_mul_f32_e32 v23, v68, v23
	v_max_f32_e32 v16, 0, v16
	v_mul_f32_e32 v84, v23, v21
	v_mul_f32_e32 v21, v85, v22
	v_cmp_gt_f32_e32 vcc, s92, v16
	v_mul_f32_e32 v22, 0x4f800000, v16
	v_add_f32_e32 v17, 1.0, v17
	v_cndmask_b32_e32 v16, v16, v22, vcc
	v_sqrt_f32_e32 v22, v16
	s_waitcnt lgkmcnt(2)
	v_add_f32_e32 v18, v18, v33
	v_rcp_f32_e32 v17, v17
	v_mul_f32_e32 v18, 0xbfb8aa3b, v18
	v_exp_f32_e32 v18, v18
	v_add_u32_e32 v23, -1, v22
	v_fma_f32 v24, -v23, v22, v16
	v_mul_f32_e32 v17, 0xc1000000, v17
	v_cmp_ge_f32_e64 s[6:7], 0, v24
	v_add_u32_e32 v24, 1, v22
	v_mul_f32_e32 v17, v17, v35
	v_add_f32_e32 v18, 1.0, v18
	v_cndmask_b32_e64 v23, v22, v23, s[6:7]
	v_fma_f32 v22, -v24, v22, v16
	v_mul_f32_e32 v17, 0x3fb8aa3b, v17
	v_rcp_f32_e32 v18, v18
	v_cmp_lt_f32_e64 s[6:7], 0, v22
	v_exp_f32_e32 v89, v17
	v_add_f32_e32 v10, v10, v31
	v_cndmask_b32_e64 v22, v23, v24, s[6:7]
	v_mul_f32_e32 v23, 0x37800000, v22
	v_mul_f32_e32 v10, 0xbfb8aa3b, v10
	v_cndmask_b32_e32 v22, v22, v23, vcc
	v_cmp_class_f32_e32 vcc, v16, v235
	v_exp_f32_e32 v10, v10
	v_mul_f32_e32 v18, v69, v18
	v_cndmask_b32_e32 v16, v22, v16, vcc
	v_fma_f32 v17, -v89, v89, 1.0
	v_fma_f32 v20, v85, v20, v84
	v_mul_f32_e32 v86, v18, v16
	v_max_f32_e32 v17, 0, v17
	v_fma_f32 v16, v87, v20, v86
	v_cmp_gt_f32_e32 vcc, s92, v17
	v_mul_f32_e32 v20, 0x4f800000, v17
	v_add_f32_e32 v10, 1.0, v10
	v_cndmask_b32_e32 v17, v17, v20, vcc
	v_sqrt_f32_e32 v20, v17
	v_rcp_f32_e32 v10, v10
	v_add_f32_e32 v19, v19, v33
	v_mul_f32_e32 v19, 0xbfb8aa3b, v19
	v_exp_f32_e32 v19, v19
	v_mul_f32_e32 v18, v87, v21
	v_add_u32_e32 v21, -1, v20
	v_mul_f32_e32 v10, 0xc1000000, v10
	v_fma_f32 v22, -v21, v20, v17
	v_mul_f32_e32 v10, v10, v35
	v_cmp_ge_f32_e64 s[6:7], 0, v22
	v_add_u32_e32 v22, 1, v20
	v_mul_f32_e32 v10, 0x3fb8aa3b, v10
	v_add_f32_e32 v19, 1.0, v19
	v_cndmask_b32_e64 v21, v20, v21, s[6:7]
	v_fma_f32 v20, -v22, v20, v17
	v_exp_f32_e32 v92, v10
	v_rcp_f32_e32 v19, v19
	v_cmp_lt_f32_e64 s[6:7], 0, v20
	v_add_f32_e32 v11, v11, v31
	v_mul_f32_e32 v11, 0xbfb8aa3b, v11
	v_cndmask_b32_e64 v20, v21, v22, s[6:7]
	v_mul_f32_e32 v21, 0x37800000, v20
	v_cndmask_b32_e32 v20, v20, v21, vcc
	v_cmp_class_f32_e32 vcc, v17, v235
	v_fma_f32 v10, -v92, v92, 1.0
	v_exp_f32_e32 v11, v11
	v_cndmask_b32_e32 v17, v20, v17, vcc
	v_mul_f32_e32 v19, v70, v19
	v_max_f32_e32 v10, 0, v10
	v_mul_f32_e32 v88, v19, v17
	v_mul_f32_e32 v17, v89, v18
	v_cmp_gt_f32_e32 vcc, s92, v10
	v_mul_f32_e32 v18, 0x4f800000, v10
	v_add_f32_e32 v11, 1.0, v11
	v_cndmask_b32_e32 v10, v10, v18, vcc
	v_sqrt_f32_e32 v18, v10
	s_waitcnt lgkmcnt(1)
; DEVI float sigmoidf_(float x) { return __builtin_amdgcn_rcpf(1.f + __expf(-x)); }
; DEVI f32x4 mfma16(bf16x8 a, bf16x8 b, f32x4 c) { return __builtin_amdgcn_mfma_f32_16x16x32_bf16(a, b, c, 0, 0, 0); }
; DEVI void lru_item(const Params& p, int l, int item, int pass) {
;     ...
;       const u16* wb = WGT + (size_t)((((l * 2 + d) * 2 + mat) * 4 + n) * 64) * 64 + 8 * g;
;       f32x4 acc[4];
; #pragma unroll
;       for (int nt = 0; nt < 4; ++nt) {
;         const bf16x8 B0 = *(const bf16x8*)(wb + (16 * nt + fr) * 64), B1 = *(const bf16x8*)(wb + (16 * nt + fr) * 64 + 32);
;         f32x4 z = {0.f, 0.f, 0.f, 0.f};
;         z = mfma16(A0, B0, z); z = mfma16(A1, B1, z); acc[nt] = z;
;     ...
;     for (int q = 0; q < 16; ++q) {
;       const int tt = d == 0 ? q : 15 - q;
;       const float r = sigmoidf_(pre[0][tt] + ba), ig = sigmoidf_(pre[1][tt] + bx);
;       const float la = -8.f * r * sp;
;       const float a = __expf(la);
;       const float om = fmaxf(1.f - a * a, 0.f);
;       const float bb = sqrtf(om) * (ig * uo[tt]);
;       av[d][tt] = a; bv[d][tt] = bb;
;       Bp = a * Bp + bb; Ap *= a;
;     }
	v_add_f32_e32 v14, v14, v33
	v_rcp_f32_e32 v11, v11
	v_mul_f32_e32 v14, 0xbfb8aa3b, v14
	v_exp_f32_e32 v14, v14
	v_add_u32_e32 v19, -1, v18
	v_fma_f32 v20, -v19, v18, v10
	v_mul_f32_e32 v11, 0xc1000000, v11
	v_cmp_ge_f32_e64 s[6:7], 0, v20
	v_add_u32_e32 v20, 1, v18
	v_mul_f32_e32 v11, v11, v35
	v_add_f32_e32 v14, 1.0, v14
	v_cndmask_b32_e64 v19, v18, v19, s[6:7]
	v_fma_f32 v18, -v20, v18, v10
	v_mul_f32_e32 v11, 0x3fb8aa3b, v11
	v_rcp_f32_e32 v14, v14
	v_cmp_lt_f32_e64 s[6:7], 0, v18
	v_exp_f32_e32 v95, v11
	v_add_f32_e32 v8, v8, v31
	v_cndmask_b32_e64 v18, v19, v20, s[6:7]
	v_mul_f32_e32 v19, 0x37800000, v18
	v_mul_f32_e32 v8, 0xbfb8aa3b, v8
	v_cndmask_b32_e32 v18, v18, v19, vcc
	v_cmp_class_f32_e32 vcc, v10, v235
	v_exp_f32_e32 v8, v8
	v_mul_f32_e32 v14, v71, v14
	v_cndmask_b32_e32 v10, v18, v10, vcc
	v_fma_f32 v11, -v95, v95, 1.0
	v_fma_f32 v16, v89, v16, v88
	v_mul_f32_e32 v91, v14, v10
	v_max_f32_e32 v11, 0, v11
	v_fma_f32 v10, v92, v16, v91
	v_cmp_gt_f32_e32 vcc, s92, v11
	v_mul_f32_e32 v16, 0x4f800000, v11
	v_add_f32_e32 v8, 1.0, v8
	v_cndmask_b32_e32 v11, v11, v16, vcc
	v_sqrt_f32_e32 v16, v11
	v_rcp_f32_e32 v8, v8
	v_add_f32_e32 v15, v15, v33
	v_mul_f32_e32 v15, 0xbfb8aa3b, v15
	v_exp_f32_e32 v15, v15
	v_mul_f32_e32 v14, v92, v17
	v_add_u32_e32 v17, -1, v16
	v_mul_f32_e32 v8, 0xc1000000, v8
	v_fma_f32 v18, -v17, v16, v11
	v_mul_f32_e32 v8, v8, v35
	v_cmp_ge_f32_e64 s[6:7], 0, v18
	v_add_u32_e32 v18, 1, v16
	v_mul_f32_e32 v8, 0x3fb8aa3b, v8
	v_add_f32_e32 v15, 1.0, v15
	v_cndmask_b32_e64 v17, v16, v17, s[6:7]
	v_fma_f32 v16, -v18, v16, v11
	v_exp_f32_e32 v101, v8
	v_rcp_f32_e32 v15, v15
	v_cmp_lt_f32_e64 s[6:7], 0, v16
	v_add_f32_e32 v9, v9, v31
	v_mul_f32_e32 v9, 0xbfb8aa3b, v9
	v_cndmask_b32_e64 v16, v17, v18, s[6:7]
	v_mul_f32_e32 v17, 0x37800000, v16
	v_exp_f32_e32 v9, v9
	v_cndmask_b32_e32 v16, v16, v17, vcc
	v_cmp_class_f32_e32 vcc, v11, v235
	v_fma_f32 v8, -v101, v101, 1.0
	v_mul_f32_e32 v15, v73, v15
	v_cndmask_b32_e32 v11, v16, v11, vcc
	v_max_f32_e32 v8, 0, v8
	v_mul_f32_e32 v93, v15, v11
	v_mul_f32_e32 v11, v95, v14
	v_cmp_gt_f32_e32 vcc, s92, v8
	v_mul_f32_e32 v14, 0x4f800000, v8
	v_add_f32_e32 v9, 1.0, v9
	v_cndmask_b32_e32 v8, v8, v14, vcc
	v_sqrt_f32_e32 v14, v8
	v_rcp_f32_e32 v9, v9
	s_waitcnt lgkmcnt(0)
	v_add_f32_e32 v12, v12, v33
	v_mul_f32_e32 v12, 0xbfb8aa3b, v12
	v_exp_f32_e32 v12, v12
	v_add_u32_e32 v15, -1, v14
	v_mul_f32_e32 v9, 0xc1000000, v9
	v_fma_f32 v16, -v15, v14, v8
	v_mul_f32_e32 v9, v9, v35
	v_cmp_ge_f32_e64 s[6:7], 0, v16
	v_add_u32_e32 v16, 1, v14
	v_mul_f32_e32 v9, 0x3fb8aa3b, v9
	v_add_f32_e32 v12, 1.0, v12
	v_cndmask_b32_e64 v15, v14, v15, s[6:7]
	v_fma_f32 v14, -v16, v14, v8
	v_exp_f32_e32 v106, v9
	v_rcp_f32_e32 v12, v12
	v_cmp_lt_f32_e64 s[6:7], 0, v14
	v_fma_f32 v10, v95, v10, v93
	v_fma_f32 v9, -v106, v106, 1.0
	v_cndmask_b32_e64 v14, v15, v16, s[6:7]
	v_mul_f32_e32 v15, 0x37800000, v14
	v_cndmask_b32_e32 v14, v14, v15, vcc
	v_cmp_class_f32_e32 vcc, v8, v235
	v_mul_f32_e32 v12, v74, v12
	v_max_f32_e32 v9, 0, v9
	v_cndmask_b32_e32 v8, v14, v8, vcc
	v_mul_f32_e32 v94, v12, v8
	v_cmp_gt_f32_e32 vcc, s92, v9
	v_mul_f32_e32 v12, 0x4f800000, v9
	v_fma_f32 v8, v101, v10, v94
	v_cndmask_b32_e32 v9, v9, v12, vcc
	v_sqrt_f32_e32 v12, v9
	v_mul_f32_e32 v10, v101, v11
	v_add_f32_e32 v11, v13, v33
	v_mul_f32_e32 v11, 0xbfb8aa3b, v11
	v_exp_f32_e32 v11, v11
	v_add_u32_e32 v13, -1, v12
	v_fma_f32 v14, -v13, v12, v9
	v_cmp_ge_f32_e64 s[6:7], 0, v14
	v_add_u32_e32 v14, 1, v12
	v_add_f32_e32 v11, 1.0, v11
	v_cndmask_b32_e64 v13, v12, v13, s[6:7]
	v_fma_f32 v12, -v14, v12, v9
	v_rcp_f32_e32 v11, v11
	v_cmp_lt_f32_e64 s[6:7], 0, v12
	s_mov_b64 s[0:1], 0x10000
	v_lshl_add_u64 v[24:25], v[28:29], 0, s[0:1]
	v_cndmask_b32_e64 v12, v13, v14, s[6:7]
	v_mul_f32_e32 v13, 0x37800000, v12
	v_cndmask_b32_e32 v12, v12, v13, vcc
	v_cmp_class_f32_e32 vcc, v9, v235
	v_mul_f32_e32 v11, v72, v11
	v_lshlrev_b32_e32 v212, 1, v107
	v_cndmask_b32_e32 v9, v12, v9, vcc
	v_mul_f32_e32 v96, v11, v9
	v_fma_f32 v9, v106, v8, v96
	v_mul_f32_e32 v8, v106, v10
	v_lshlrev_b32_e32 v10, 3, v76
	v_add_u32_e32 v76, 0, v10
	v_add_u32_e32 v10, 0x15b00, v76
	ds_write_b64 v10, v[8:9]
	v_lshl_add_u64 v[12:13], v[24:25], 0, v[212:213]
	s_nop 0
	s_nop 0
	s_nop 0
	s_waitcnt vmcnt(18)
	v_mfma_f32_16x16x32_bf16 v[8:11], v[4:7], v[152:155], 0
	v_mov_b32_e32 v35, v213
	v_lshl_add_u64 v[16:17], v[24:25], 0, v[34:35]
	v_mov_b32_e32 v31, v213
	s_waitcnt vmcnt(17)
; DEVI f32x4 mfma16(bf16x8 a, bf16x8 b, f32x4 c) { return __builtin_amdgcn_mfma_f32_16x16x32_bf16(a, b, c, 0, 0, 0); }
; DEVI void lru_item(const Params& p, int l, int item, int pass) {
;     ...
;       const u16* wb = WGT + (size_t)((((l * 2 + d) * 2 + mat) * 4 + n) * 64) * 64 + 8 * g;
;       f32x4 acc[4];
; #pragma unroll
;       for (int nt = 0; nt < 4; ++nt) {
;         const bf16x8 B0 = *(const bf16x8*)(wb + (16 * nt + fr) * 64), B1 = *(const bf16x8*)(wb + (16 * nt + fr) * 64 + 32);
;         f32x4 z = {0.f, 0.f, 0.f, 0.f};
;         z = mfma16(A0, B0, z); z = mfma16(A1, B1, z); acc[nt] = z;
;       }
;       asm volatile("s_waitcnt lgkmcnt(0)" ::: "memory");
; #pragma unroll
;       for (int nt = 0; nt < 4; ++nt)
; #pragma unroll
;         for (int j = 0; j < 4; ++j) exw[(4 * g + j) * 65 + 16 * nt + fr] = acc[nt][j];
;       asm volatile("s_waitcnt lgkmcnt(0)" ::: "memory");
; #pragma unroll
;       for (int tt = 0; tt < 16; ++tt) pre[mat][tt] = exw[tt * 65 + lane];
;     }
;     const float ba = p.in[14][(l * 2 + d) * 256 + c], bx = p.in[16][(l * 2 + d) * 256 + c];
;     const float lam = p.in[17][(l * 2 + d) * 256 + c];
;     const float exl = __expf(-lam); const float sp = exl < 0.03f ? exl * (1.f - exl * (0.5f - exl * (0.33333334f - 0.25f * exl))) : __logf(1.f + exl);
	v_mfma_f32_16x16x32_bf16 v[8:11], v[0:3], v[156:159], v[8:11]
	s_nop 0
	s_nop 0
	s_nop 0
	v_lshl_add_u64 v[20:21], v[24:25], 0, v[30:31]
	v_mov_b32_e32 v33, v213
	s_waitcnt vmcnt(16)
	v_mfma_f32_16x16x32_bf16 v[12:15], v[4:7], v[160:163], 0
	v_lshl_add_u64 v[24:25], v[24:25], 0, v[32:33]
	s_mov_b64 s[0:1], 0x18000
	s_waitcnt vmcnt(15)
	v_mfma_f32_16x16x32_bf16 v[12:15], v[0:3], v[164:167], v[12:15]
	s_nop 0
	s_nop 0
	s_nop 0
	s_waitcnt vmcnt(14)
	v_mfma_f32_16x16x32_bf16 v[16:19], v[4:7], v[168:171], 0
	s_waitcnt vmcnt(13)
	v_mfma_f32_16x16x32_bf16 v[16:19], v[0:3], v[172:175], v[16:19]
	s_nop 0
	s_nop 0
	s_nop 0
	s_waitcnt lgkmcnt(0)
	s_waitcnt vmcnt(12)
	v_mfma_f32_16x16x32_bf16 v[20:23], v[4:7], v[176:179], 0
	s_waitcnt vmcnt(11)
	v_mfma_f32_16x16x32_bf16 v[20:23], v[0:3], v[180:183], v[20:23]
	v_add_u32_e32 v24, v90, v108
	v_add_u32_e32 v90, 0xd800, v24
	v_add_u32_e32 v107, 0xdc00, v24
	ds_write2_b32 v90, v8, v12 offset0:64 offset1:80
	ds_write2_b32 v90, v9, v13 offset0:129 offset1:145
	ds_write2_b32 v90, v10, v14 offset0:194 offset1:210
	ds_write2_b32 v107, v11, v15 offset0:3 offset1:19
	s_nop 0
	ds_write2_b32 v90, v16, v20 offset0:96 offset1:112
	ds_write2_b32 v90, v17, v21 offset0:161 offset1:177
	ds_write2_b32 v90, v18, v22 offset0:226 offset1:242
	ds_write2_b32 v107, v19, v23 offset0:35 offset1:51
	v_lshl_add_u64 v[18:19], v[28:29], 0, s[0:1]
	s_waitcnt lgkmcnt(0)
	v_lshl_add_u64 v[22:23], v[18:19], 0, v[212:213]
	ds_read2_b32 v[8:9], v97 offset0:64 offset1:129
	ds_read2_b32 v[10:11], v98 offset0:66 offset1:131
	ds_read2_b32 v[12:13], v99 offset0:68 offset1:133
	ds_read2_b32 v[14:15], v100 offset0:70 offset1:135
	ds_read2_b32 v[16:17], v102 offset0:72 offset1:137
	ds_read2_b32 v[20:21], v103 offset0:74 offset1:139
	ds_read2_b32 v[24:25], v104 offset0:76 offset1:141
	ds_read2_b32 v[42:43], v105 offset0:78 offset1:143
	s_nop 0
	s_nop 0
	s_waitcnt vmcnt(10)
	v_mfma_f32_16x16x32_bf16 v[26:29], v[4:7], v[184:187], 0
	v_lshl_add_u64 v[22:23], v[18:19], 0, v[34:35]
	s_mov_b32 s0, 0x3cf5c28f
	s_waitcnt vmcnt(9)
	v_mfma_f32_16x16x32_bf16 v[26:29], v[0:3], v[188:191], v[26:29]
	s_nop 0
	s_nop 0
	v_lshl_add_u64 v[22:23], v[18:19], 0, v[30:31]
	v_lshl_add_u64 v[18:19], v[18:19], 0, v[32:33]
	s_waitcnt vmcnt(8)
	v_mfma_f32_16x16x32_bf16 v[108:111], v[4:7], v[192:195], 0
	s_waitcnt vmcnt(7)
	v_mfma_f32_16x16x32_bf16 v[108:111], v[0:3], v[196:199], v[108:111]
	s_nop 0
	s_nop 0
	s_waitcnt vmcnt(6)
	v_mfma_f32_16x16x32_bf16 v[112:115], v[4:7], v[200:203], 0
	s_waitcnt vmcnt(5)
	v_mfma_f32_16x16x32_bf16 v[112:115], v[0:3], v[204:207], v[112:115]
	s_nop 0
	s_nop 0
	s_waitcnt lgkmcnt(0)
	s_waitcnt vmcnt(4)
	v_mfma_f32_16x16x32_bf16 v[4:7], v[4:7], v[208:211], 0
	s_waitcnt vmcnt(3)
	v_mfma_f32_16x16x32_bf16 v[0:3], v[0:3], v[144:147], v[4:7]
	ds_write2_b32 v90, v26, v108 offset0:64 offset1:80
	ds_write2_b32 v90, v27, v109 offset0:129 offset1:145
	ds_write2_b32 v90, v28, v110 offset0:194 offset1:210
	ds_write2_b32 v107, v29, v111 offset0:3 offset1:19
	s_nop 3
	ds_write2_b32 v90, v112, v0 offset0:96 offset1:112
	ds_write2_b32 v90, v113, v1 offset0:161 offset1:177
	ds_write2_b32 v90, v114, v2 offset0:226 offset1:242
	ds_write2_b32 v107, v115, v3 offset0:35 offset1:51
	s_waitcnt lgkmcnt(0)
	ds_read2_b32 v[0:1], v97 offset0:64 offset1:129
	ds_read2_b32 v[2:3], v98 offset0:66 offset1:131
	ds_read2_b32 v[4:5], v99 offset0:68 offset1:133
	ds_read2_b32 v[6:7], v100 offset0:70 offset1:135
	ds_read2_b32 v[18:19], v102 offset0:72 offset1:137
	ds_read2_b32 v[22:23], v103 offset0:74 offset1:139
	ds_read2_b32 v[26:27], v104 offset0:76 offset1:141
	ds_read2_b32 v[28:29], v105 offset0:78 offset1:143
	global_load_dword v32, v[36:37], off offset:1024
	global_load_dword v31, v[38:39], off offset:1024
	global_load_dword v30, v[40:41], off offset:1024
	s_waitcnt vmcnt(0)
	v_mul_f32_e32 v30, 0xbfb8aa3b, v30
	v_exp_f32_e32 v30, v30
	s_nop 0
	v_cmp_ngt_f32_e32 vcc, s0, v30
	s_and_saveexec_b64 s[0:1], vcc
	s_xor_b64 s[8:9], exec, s[0:1]
	s_cbranch_execz .LBB0_1561
	v_add_f32_e32 v30, 1.0, v30
	v_cmp_gt_f32_e32 vcc, s63, v30
	s_mov_b32 s0, 0x3f317217
	s_nop 0
	v_cndmask_b32_e64 v33, 0, 32, vcc
	v_ldexp_f32 v30, v30, v33
	v_log_f32_e32 v30, v30
	s_nop 0
	v_mul_f32_e32 v33, 0x3f317217, v30
	v_fma_f32 v33, v30, s0, -v33
	v_fmac_f32_e32 v33, 0x3377d1cf, v30
	s_mov_b32 s0, 0x7f800000
	v_fmac_f32_e32 v33, 0x3f317217, v30
	v_cmp_lt_f32_e64 s[6:7], |v30|, s0
	s_nop 1
	v_cndmask_b32_e64 v30, v30, v33, s[6:7]
	v_cndmask_b32_e32 v33, 0, v225, vcc
	v_sub_f32_e32 v33, v30, v33

; DEVI unsigned pk_bf16(float lo, float hi) { unsigned r; asm volatile("v_cvt_pk_bf16_f32 %0, %1, %2" : "=v"(r) : "v"(lo), "v"(hi)); return r; }
; DEVI float sigmoidf_(float x) { return __builtin_amdgcn_rcpf(1.f + __expf(-x)); }
; template <class Epi>
; DEVI void gemm_phase(const Params& p, const u16* __restrict__ A, const u16* __restrict__ Bt, const int M, const int N, const int K, const int Msplit, const Epi& epi) {
;     ...
; #pragma unroll
;       for (int ai = 0; ai < 2; ++ai)
; #pragma unroll
;         for (int bj = 0; bj < 2; ++bj) {
;           const int colb = bcol + bj * HALF + wc2 * 32;
;           typename Epi::Pre pre;
;           if constexpr (Epi::NRM || Epi::SQ) epi.preload(pre, brow, colb, wr2, fr2, fq2, nrm, slcur);
; #pragma unroll
;           for (int m = 0; m < 4; ++m) {
;             const int rloc = ai * HALF + wr2 * 64 + m * 16;
;             if constexpr (Epi::SQ) epi(brow + rloc + fr2, colb, fq2, acc[ai][bj][m][0], acc[ai][bj][m][1], sq[ai * 4 + m], slcur, pre);
;             else if constexpr (Epi::TR) { float rv = 1.f; if (nrm) rv = rl[rloc + fr2]; epi(brow + rloc + fr2, colb, fq2, acc[ai][bj][m][0], acc[ai][bj][m][1], rv, nrm, pre); }
;             else { f32x4 rv = {1.f, 1.f, 1.f, 1.f}; if (nrm) rv = *(const f32x4*)(rl + rloc + fq2 * 4); epi(brow + rloc + fq2 * 4, colb, fr2, acc[ai][bj][m][0], acc[ai][bj][m][1], rv, nrm, pre); }
;           }
;   DEVI void operator()(int row, int colb, int fq, const f32x4& a0, const f32x4& a1, const float rinv, const bool nrm, const Pre& q) const {
;     const int oc = (colb >> 5) * 16 + 4 * fq;
;     f32x4 xa = a0, xb = a1;
;     if (nrm) {
; #pragma unroll
;       for (int j = 0; j < 4; ++j) { xa[j] = xa[j] * rinv + q.sa[j]; xb[j] = xb[j] * rinv + q.sb[j]; }
;     }
;     float v[4];
; #pragma unroll
;     for (int j = 0; j < 4; ++j) { const float a = xa[j]; v[j] = a * sigmoidf_(a) * xb[j]; }
;     uint2 o; o.x = pk_bf16(v[0], v[1]); o.y = pk_bf16(v[2], v[3]);
;     *(uint2*)(act + (size_t)row * DFF + oc) = o;
;   }
.LBB0_1985:
	v_mbcnt_lo_u32_b32 v208, -1, 0
	v_mbcnt_hi_u32_b32 v208, -1, v208
	s_lshr_b32 s52, s33, 6
	s_lshr_b32 s53, s52, 2
	s_and_b32 s52, s52, 3
	s_mul_i32 s53, s53, 0x58000
	s_lshl_b32 s52, s52, 5
	s_add_u32 s52, s52, s53
	v_and_b32_e32 v209, 15, v208
	v_lshrrev_b32_e32 v208, 4, v208
	v_mul_u32_u24_e32 v209, 0x1600, v209
	v_lshl_add_u32 v208, v208, 3, s52
	v_add_u32_e32 v144, v208, v209
	v_add_u32_e32 v145, 0x16000, v144
	v_add_u32_e32 v146, 0x2c000, v144
	v_add_u32_e32 v147, 0x42000, v144
	v_mov_b32_e32 v148, 1.0
	v_mov_b32_e32 v149, 1.0
	v_mov_b32_e32 v206, 0xbfb8aa3b
	v_mov_b32_e32 v207, 0xbfb8aa3b
	s_mul_i32 s54, s20, 0x1600
	s_add_u32 s54, s54, s22
	s_add_u32 s44, s60, s54
	s_addc_u32 s45, s61, 0
	s_add_u32 s46, s44, 0xb0000
	s_addc_u32 s47, s45, 0
	s_mov_b32 s21, s37
	s_mov_b32 s16, s40
	s_mov_b32 s20, s41
	v_pk_mul_f32 v[128:129], v[120:121], v[206:207]
	v_pk_mul_f32 v[130:131], v[122:123], v[206:207]
	v_pk_mul_f32 v[136:137], v[112:113], v[206:207]
	v_pk_mul_f32 v[138:139], v[114:115], v[206:207]
	v_exp_f32_e32 v128, v128
	v_exp_f32_e32 v129, v129
	v_exp_f32_e32 v130, v130
	v_exp_f32_e32 v131, v131
	v_exp_f32_e32 v136, v136
	v_exp_f32_e32 v137, v137
	v_exp_f32_e32 v138, v138
	v_exp_f32_e32 v139, v139
	v_pk_add_f32 v[128:129], v[148:149], v[128:129]
	v_pk_add_f32 v[130:131], v[148:149], v[130:131]
	v_pk_add_f32 v[136:137], v[148:149], v[136:137]
	v_pk_add_f32 v[138:139], v[148:149], v[138:139]
	v_rcp_f32_e32 v128, v128
	v_rcp_f32_e32 v129, v129
	v_rcp_f32_e32 v130, v130
	v_rcp_f32_e32 v131, v131
	v_rcp_f32_e32 v136, v136
	v_rcp_f32_e32 v137, v137
	v_rcp_f32_e32 v138, v138
	v_rcp_f32_e32 v139, v139
	v_pk_mul_f32 v[120:121], v[120:121], v[128:129]
	v_pk_mul_f32 v[122:123], v[122:123], v[130:131]
	v_pk_mul_f32 v[112:113], v[112:113], v[136:137]
	v_pk_mul_f32 v[114:115], v[114:115], v[138:139]
	v_pk_mul_f32 v[120:121], v[124:125], v[120:121]
	v_pk_mul_f32 v[122:123], v[126:127], v[122:123]
	v_pk_mul_f32 v[112:113], v[116:117], v[112:113]
	v_pk_mul_f32 v[114:115], v[118:119], v[114:115]
	v_cvt_pk_bf16_f32 v124, v120, v121
	v_cvt_pk_bf16_f32 v125, v122, v123
	v_cvt_pk_bf16_f32 v116, v112, v113
	v_cvt_pk_bf16_f32 v117, v114, v115
	global_store_dwordx2 v144, v[124:125], s[44:45]
	global_store_dwordx2 v145, v[116:117], s[44:45]
	v_pk_mul_f32 v[128:129], v[104:105], v[206:207]
	v_pk_mul_f32 v[130:131], v[106:107], v[206:207]
	v_pk_mul_f32 v[136:137], v[96:97], v[206:207]
	v_pk_mul_f32 v[138:139], v[98:99], v[206:207]
	v_exp_f32_e32 v128, v128
	v_exp_f32_e32 v129, v129
	v_exp_f32_e32 v130, v130
	v_exp_f32_e32 v131, v131
	v_exp_f32_e32 v136, v136
	v_exp_f32_e32 v137, v137
	v_exp_f32_e32 v138, v138
	v_exp_f32_e32 v139, v139
	v_pk_add_f32 v[128:129], v[148:149], v[128:129]
	v_pk_add_f32 v[130:131], v[148:149], v[130:131]
	v_pk_add_f32 v[136:137], v[148:149], v[136:137]
	v_pk_add_f32 v[138:139], v[148:149], v[138:139]
	v_rcp_f32_e32 v128, v128
	v_rcp_f32_e32 v129, v129
	v_rcp_f32_e32 v130, v130
	v_rcp_f32_e32 v131, v131
	v_rcp_f32_e32 v136, v136
	v_rcp_f32_e32 v137, v137
	v_rcp_f32_e32 v138, v138
	v_rcp_f32_e32 v139, v139
	v_pk_mul_f32 v[104:105], v[104:105], v[128:129]
	v_pk_mul_f32 v[106:107], v[106:107], v[130:131]
	v_pk_mul_f32 v[96:97], v[96:97], v[136:137]
	v_pk_mul_f32 v[98:99], v[98:99], v[138:139]
	v_pk_mul_f32 v[104:105], v[108:109], v[104:105]
	v_pk_mul_f32 v[106:107], v[110:111], v[106:107]
	v_pk_mul_f32 v[96:97], v[100:101], v[96:97]
	v_pk_mul_f32 v[98:99], v[102:103], v[98:99]
	v_cvt_pk_bf16_f32 v108, v104, v105
	v_cvt_pk_bf16_f32 v109, v106, v107
	v_cvt_pk_bf16_f32 v100, v96, v97
	v_cvt_pk_bf16_f32 v101, v98, v99
	global_store_dwordx2 v146, v[108:109], s[44:45]
	global_store_dwordx2 v147, v[100:101], s[44:45]
	v_pk_mul_f32 v[128:129], v[88:89], v[206:207]
	v_pk_mul_f32 v[130:131], v[90:91], v[206:207]
	v_pk_mul_f32 v[136:137], v[80:81], v[206:207]
	v_pk_mul_f32 v[138:139], v[82:83], v[206:207]
	v_exp_f32_e32 v128, v128
	v_exp_f32_e32 v129, v129
	v_exp_f32_e32 v130, v130
	v_exp_f32_e32 v131, v131
	v_exp_f32_e32 v136, v136
	v_exp_f32_e32 v137, v137
	v_exp_f32_e32 v138, v138
	v_exp_f32_e32 v139, v139
	v_pk_add_f32 v[128:129], v[148:149], v[128:129]
	v_pk_add_f32 v[130:131], v[148:149], v[130:131]
	v_pk_add_f32 v[136:137], v[148:149], v[136:137]
	v_pk_add_f32 v[138:139], v[148:149], v[138:139]
	v_rcp_f32_e32 v128, v128
	v_rcp_f32_e32 v129, v129
	v_rcp_f32_e32 v130, v130
	v_rcp_f32_e32 v131, v131
	v_rcp_f32_e32 v136, v136
	v_rcp_f32_e32 v137, v137
	v_rcp_f32_e32 v138, v138
	v_rcp_f32_e32 v139, v139
	v_pk_mul_f32 v[88:89], v[88:89], v[128:129]
	v_pk_mul_f32 v[90:91], v[90:91], v[130:131]
	v_pk_mul_f32 v[80:81], v[80:81], v[136:137]
	v_pk_mul_f32 v[82:83], v[82:83], v[138:139]
	v_pk_mul_f32 v[88:89], v[92:93], v[88:89]
	v_pk_mul_f32 v[90:91], v[94:95], v[90:91]
	v_pk_mul_f32 v[80:81], v[84:85], v[80:81]
	v_pk_mul_f32 v[82:83], v[86:87], v[82:83]
	v_cvt_pk_bf16_f32 v92, v88, v89
	v_cvt_pk_bf16_f32 v93, v90, v91
	v_cvt_pk_bf16_f32 v84, v80, v81
	v_cvt_pk_bf16_f32 v85, v82, v83
	global_store_dwordx2 v144, v[92:93], s[44:45] offset:128
	global_store_dwordx2 v145, v[84:85], s[44:45] offset:128
	v_pk_mul_f32 v[128:129], v[72:73], v[206:207]
	v_pk_mul_f32 v[130:131], v[74:75], v[206:207]
	v_pk_mul_f32 v[136:137], v[64:65], v[206:207]
	v_pk_mul_f32 v[138:139], v[66:67], v[206:207]
	v_exp_f32_e32 v128, v128
	v_exp_f32_e32 v129, v129
	v_exp_f32_e32 v130, v130
	v_exp_f32_e32 v131, v131
	v_exp_f32_e32 v136, v136
	v_exp_f32_e32 v137, v137
	v_exp_f32_e32 v138, v138
	v_exp_f32_e32 v139, v139
	v_pk_add_f32 v[128:129], v[148:149], v[128:129]
	v_pk_add_f32 v[130:131], v[148:149], v[130:131]
	v_pk_add_f32 v[136:137], v[148:149], v[136:137]
; DEVI unsigned pk_bf16(float lo, float hi) { unsigned r; asm volatile("v_cvt_pk_bf16_f32 %0, %1, %2" : "=v"(r) : "v"(lo), "v"(hi)); return r; }
; DEVI float sigmoidf_(float x) { return __builtin_amdgcn_rcpf(1.f + __expf(-x)); }
;   DEVI void operator()(int row, int colb, int fq, const f32x4& a0, const f32x4& a1, const float rinv, const bool nrm, const Pre& q) const {
;     const int oc = (colb >> 5) * 16 + 4 * fq;
;     f32x4 xa = a0, xb = a1;
;     if (nrm) {
; #pragma unroll
;       for (int j = 0; j < 4; ++j) { xa[j] = xa[j] * rinv + q.sa[j]; xb[j] = xb[j] * rinv + q.sb[j]; }
;     }
;     float v[4];
; #pragma unroll
;     for (int j = 0; j < 4; ++j) { const float a = xa[j]; v[j] = a * sigmoidf_(a) * xb[j]; }
;     uint2 o; o.x = pk_bf16(v[0], v[1]); o.y = pk_bf16(v[2], v[3]);
;     *(uint2*)(act + (size_t)row * DFF + oc) = o;
;   }
	v_pk_add_f32 v[138:139], v[148:149], v[138:139]
	v_rcp_f32_e32 v128, v128
	v_rcp_f32_e32 v129, v129
	v_rcp_f32_e32 v130, v130
	v_rcp_f32_e32 v131, v131
	v_rcp_f32_e32 v136, v136
	v_rcp_f32_e32 v137, v137
	v_rcp_f32_e32 v138, v138
	v_rcp_f32_e32 v139, v139
	v_pk_mul_f32 v[72:73], v[72:73], v[128:129]
	v_pk_mul_f32 v[74:75], v[74:75], v[130:131]
	v_pk_mul_f32 v[64:65], v[64:65], v[136:137]
	v_pk_mul_f32 v[66:67], v[66:67], v[138:139]
	v_pk_mul_f32 v[72:73], v[76:77], v[72:73]
	v_pk_mul_f32 v[74:75], v[78:79], v[74:75]
	v_pk_mul_f32 v[64:65], v[68:69], v[64:65]
	v_pk_mul_f32 v[66:67], v[70:71], v[66:67]
	v_cvt_pk_bf16_f32 v76, v72, v73
	v_cvt_pk_bf16_f32 v77, v74, v75
	v_cvt_pk_bf16_f32 v68, v64, v65
	v_cvt_pk_bf16_f32 v69, v66, v67
	global_store_dwordx2 v146, v[76:77], s[44:45] offset:128
	global_store_dwordx2 v147, v[68:69], s[44:45] offset:128
	v_pk_mul_f32 v[128:129], v[56:57], v[206:207]
	v_pk_mul_f32 v[130:131], v[58:59], v[206:207]
	v_pk_mul_f32 v[136:137], v[48:49], v[206:207]
	v_pk_mul_f32 v[138:139], v[50:51], v[206:207]
	v_exp_f32_e32 v128, v128
	v_exp_f32_e32 v129, v129
	v_exp_f32_e32 v130, v130
	v_exp_f32_e32 v131, v131
	v_exp_f32_e32 v136, v136
	v_exp_f32_e32 v137, v137
	v_exp_f32_e32 v138, v138
	v_exp_f32_e32 v139, v139
	v_pk_add_f32 v[128:129], v[148:149], v[128:129]
	v_pk_add_f32 v[130:131], v[148:149], v[130:131]
	v_pk_add_f32 v[136:137], v[148:149], v[136:137]
	v_pk_add_f32 v[138:139], v[148:149], v[138:139]
	v_rcp_f32_e32 v128, v128
	v_rcp_f32_e32 v129, v129
	v_rcp_f32_e32 v130, v130
	v_rcp_f32_e32 v131, v131
	v_rcp_f32_e32 v136, v136
	v_rcp_f32_e32 v137, v137
	v_rcp_f32_e32 v138, v138
	v_rcp_f32_e32 v139, v139
	v_pk_mul_f32 v[56:57], v[56:57], v[128:129]
	v_pk_mul_f32 v[58:59], v[58:59], v[130:131]
	v_pk_mul_f32 v[48:49], v[48:49], v[136:137]
	v_pk_mul_f32 v[50:51], v[50:51], v[138:139]
	v_pk_mul_f32 v[56:57], v[60:61], v[56:57]
	v_pk_mul_f32 v[58:59], v[62:63], v[58:59]
	v_pk_mul_f32 v[48:49], v[52:53], v[48:49]
	v_pk_mul_f32 v[50:51], v[54:55], v[50:51]
	v_cvt_pk_bf16_f32 v60, v56, v57
	v_cvt_pk_bf16_f32 v61, v58, v59
	v_cvt_pk_bf16_f32 v52, v48, v49
	v_cvt_pk_bf16_f32 v53, v50, v51
	global_store_dwordx2 v144, v[60:61], s[46:47]
	global_store_dwordx2 v145, v[52:53], s[46:47]
	v_pk_mul_f32 v[128:129], v[40:41], v[206:207]
	v_pk_mul_f32 v[130:131], v[42:43], v[206:207]
	v_pk_mul_f32 v[136:137], v[32:33], v[206:207]
	v_pk_mul_f32 v[138:139], v[34:35], v[206:207]
	v_exp_f32_e32 v128, v128
	v_exp_f32_e32 v129, v129
	v_exp_f32_e32 v130, v130
	v_exp_f32_e32 v131, v131
	v_exp_f32_e32 v136, v136
	v_exp_f32_e32 v137, v137
	v_exp_f32_e32 v138, v138
	v_exp_f32_e32 v139, v139
	v_pk_add_f32 v[128:129], v[148:149], v[128:129]
	v_pk_add_f32 v[130:131], v[148:149], v[130:131]
	v_pk_add_f32 v[136:137], v[148:149], v[136:137]
	v_pk_add_f32 v[138:139], v[148:149], v[138:139]
	v_rcp_f32_e32 v128, v128
	v_rcp_f32_e32 v129, v129
	v_rcp_f32_e32 v130, v130
	v_rcp_f32_e32 v131, v131
	v_rcp_f32_e32 v136, v136
	v_rcp_f32_e32 v137, v137
	v_rcp_f32_e32 v138, v138
	v_rcp_f32_e32 v139, v139
	v_pk_mul_f32 v[40:41], v[40:41], v[128:129]
	v_pk_mul_f32 v[42:43], v[42:43], v[130:131]
	v_pk_mul_f32 v[32:33], v[32:33], v[136:137]
	v_pk_mul_f32 v[34:35], v[34:35], v[138:139]
	v_pk_mul_f32 v[40:41], v[44:45], v[40:41]
	v_pk_mul_f32 v[42:43], v[46:47], v[42:43]
	v_pk_mul_f32 v[32:33], v[36:37], v[32:33]
	v_pk_mul_f32 v[34:35], v[38:39], v[34:35]
	v_cvt_pk_bf16_f32 v44, v40, v41
	v_cvt_pk_bf16_f32 v45, v42, v43
	v_cvt_pk_bf16_f32 v36, v32, v33
	v_cvt_pk_bf16_f32 v37, v34, v35
	global_store_dwordx2 v146, v[44:45], s[46:47]
	global_store_dwordx2 v147, v[36:37], s[46:47]
	v_pk_mul_f32 v[128:129], v[24:25], v[206:207]
	v_pk_mul_f32 v[130:131], v[26:27], v[206:207]
	v_pk_mul_f32 v[136:137], v[16:17], v[206:207]
	v_pk_mul_f32 v[138:139], v[18:19], v[206:207]
	v_exp_f32_e32 v128, v128
	v_exp_f32_e32 v129, v129
	v_exp_f32_e32 v130, v130
	v_exp_f32_e32 v131, v131
	v_exp_f32_e32 v136, v136
	v_exp_f32_e32 v137, v137
	v_exp_f32_e32 v138, v138
	v_exp_f32_e32 v139, v139
	v_pk_add_f32 v[128:129], v[148:149], v[128:129]
	v_pk_add_f32 v[130:131], v[148:149], v[130:131]
	v_pk_add_f32 v[136:137], v[148:149], v[136:137]
	v_pk_add_f32 v[138:139], v[148:149], v[138:139]
	v_rcp_f32_e32 v128, v128
	v_rcp_f32_e32 v129, v129
	v_rcp_f32_e32 v130, v130
	v_rcp_f32_e32 v131, v131
	v_rcp_f32_e32 v136, v136
	v_rcp_f32_e32 v137, v137
	v_rcp_f32_e32 v138, v138
	v_rcp_f32_e32 v139, v139
	v_pk_mul_f32 v[24:25], v[24:25], v[128:129]
	v_pk_mul_f32 v[26:27], v[26:27], v[130:131]
	v_pk_mul_f32 v[16:17], v[16:17], v[136:137]
	v_pk_mul_f32 v[18:19], v[18:19], v[138:139]
	v_pk_mul_f32 v[24:25], v[28:29], v[24:25]
	v_pk_mul_f32 v[26:27], v[30:31], v[26:27]
	v_pk_mul_f32 v[16:17], v[20:21], v[16:17]
	v_pk_mul_f32 v[18:19], v[22:23], v[18:19]
	v_cvt_pk_bf16_f32 v28, v24, v25
	v_cvt_pk_bf16_f32 v29, v26, v27
	v_cvt_pk_bf16_f32 v20, v16, v17
	v_cvt_pk_bf16_f32 v21, v18, v19
	global_store_dwordx2 v144, v[28:29], s[46:47] offset:128
	global_store_dwordx2 v145, v[20:21], s[46:47] offset:128
	v_pk_mul_f32 v[128:129], v[8:9], v[206:207]
	v_pk_mul_f32 v[130:131], v[10:11], v[206:207]
	v_pk_mul_f32 v[136:137], v[0:1], v[206:207]
	v_pk_mul_f32 v[138:139], v[2:3], v[206:207]
	v_exp_f32_e32 v128, v128
	v_exp_f32_e32 v129, v129
	v_exp_f32_e32 v130, v130
	v_exp_f32_e32 v131, v131
	v_exp_f32_e32 v136, v136
	v_exp_f32_e32 v137, v137
	v_exp_f32_e32 v138, v138
	v_exp_f32_e32 v139, v139
	v_pk_add_f32 v[128:129], v[148:149], v[128:129]
	v_pk_add_f32 v[130:131], v[148:149], v[130:131]
	v_pk_add_f32 v[136:137], v[148:149], v[136:137]
	v_pk_add_f32 v[138:139], v[148:149], v[138:139]
	v_rcp_f32_e32 v128, v128
	v_rcp_f32_e32 v129, v129
	v_rcp_f32_e32 v130, v130
	v_rcp_f32_e32 v131, v131
	v_rcp_f32_e32 v136, v136
	v_rcp_f32_e32 v137, v137
	v_rcp_f32_e32 v138, v138
	v_rcp_f32_e32 v139, v139
	v_pk_mul_f32 v[8:9], v[8:9], v[128:129]
	v_pk_mul_f32 v[10:11], v[10:11], v[130:131]
	v_pk_mul_f32 v[0:1], v[0:1], v[136:137]
	v_pk_mul_f32 v[2:3], v[2:3], v[138:139]
	v_pk_mul_f32 v[8:9], v[12:13], v[8:9]
	v_pk_mul_f32 v[10:11], v[14:15], v[10:11]
	v_pk_mul_f32 v[0:1], v[4:5], v[0:1]
	v_pk_mul_f32 v[2:3], v[6:7], v[2:3]
	v_cvt_pk_bf16_f32 v12, v8, v9
	v_cvt_pk_bf16_f32 v13, v10, v11
	v_cvt_pk_bf16_f32 v4, v0, v1
	v_cvt_pk_bf16_f32 v5, v2, v3
	global_store_dwordx2 v146, v[12:13], s[46:47] offset:128
	global_store_dwordx2 v147, v[4:5], s[46:47] offset:128
	s_andn2_b64 vcc, exec, s[10:11]
	s_cbranch_vccz .LBB0_2006
